# c3: UPD state loads issued after gla_b loads and kept in flight; c3 epilogue gla_norm loads hoisted
# speedup vs baseline: 1.0240x; 1.0037x over previous
; __device__ __forceinline__ void gla_c3(const Args& a, int l, unsigned char* sm, const bf16_t* __restrict__ PC, const bf16_t* __restrict__ PLR, const bf16_t* __restrict__ UPD, bf16_t* __restrict__ OC) {
;     ...
;         float* Of = (float*)sm;
; #pragma unroll
;         for (int mi = 0; mi < 2; ++mi)
; #pragma unroll
;             for (int e = 0; e < 16; ++e) { const int i = 32 * mi + (e & 3) + 8 * (e >> 2) + 4 * h; Of[i * 260 + 32 * wid + r] = accO[mi][e]; }
;         __syncthreads();
;         bf16_t rgv[8][4];
; #pragma unroll
;         for (int rr = 0; rr < 8; ++rr)
; #pragma unroll
;             for (int q = 0; q < 4; ++q) rgv[rr][q] = PC[(size_t)(t0 + 8 * wid + rr) * 3072 + 2048 + hd * 256 + lane + 64 * q];
; #pragma unroll
;         for (int rr = 0; rr < 8; ++rr) {
;             const int i = 8 * wid + rr, t = t0 + i;
;             float v[4]; float ss = 0.f;
; #pragma unroll
;             for (int q = 0; q < 4; ++q) { v[q] = Of[i * 260 + lane + 64 * q]; ss += v[q] * v[q]; }
; #pragma unroll
;             for (int o = 32; o >= 1; o >>= 1) ss += __shfl_xor(ss, o);
;             const float sc = rsqrtf(ss * (1.f / 256.f) + EPS_);
.LBB0_453:
	v_readlane_b32 s28, v246, 29
	v_readlane_b32 s29, v246, 30
	ds_write_b32 v107, v0
	ds_write_b32 v107, v1 offset:1040
	ds_write_b32 v107, v2 offset:2080
	ds_write_b32 v107, v3 offset:3120
	ds_write_b32 v107, v4 offset:8320
	ds_write_b32 v107, v5 offset:9360
	ds_write_b32 v107, v6 offset:10400
	ds_write_b32 v107, v7 offset:11440
	ds_write_b32 v107, v8 offset:16640
	ds_write_b32 v107, v9 offset:17680
	ds_write_b32 v107, v10 offset:18720
	ds_write_b32 v107, v11 offset:19760
	ds_write_b32 v107, v12 offset:24960
	ds_write_b32 v107, v13 offset:26000
	ds_write_b32 v107, v14 offset:27040
	ds_write_b32 v107, v15 offset:28080
	ds_write_b32 v107, v16 offset:33280
	ds_write_b32 v107, v17 offset:34320
	ds_write_b32 v107, v18 offset:35360
	ds_write_b32 v107, v19 offset:36400
	ds_write_b32 v107, v20 offset:41600
	ds_write_b32 v107, v21 offset:42640
	ds_write_b32 v107, v22 offset:43680
	ds_write_b32 v107, v23 offset:44720
	ds_write_b32 v107, v24 offset:49920
	ds_write_b32 v107, v25 offset:50960
	ds_write_b32 v107, v26 offset:52000
	ds_write_b32 v107, v27 offset:53040
	ds_write_b32 v107, v28 offset:58240
	ds_write_b32 v107, v29 offset:59280
	ds_write_b32 v107, v30 offset:60320
	ds_write_b32 v107, v31 offset:61360
	v_add_u32_e32 v0, s44, v95
	v_mov_b64_e32 v[14:15], s[28:29]
	s_movk_i32 s6, 0x1800
	v_mad_i64_i32 v[2:3], s[2:3], v0, s6, v[14:15]
	v_readlane_b32 s2, v244, 6
	v_readlane_b32 s3, v244, 7
	s_lshl_b64 s[4:5], s[2:3], 1
	v_lshl_add_u64 v[2:3], v[2:3], 0, s[4:5]
	v_mov_b32_e32 v93, v65
	v_lshl_add_u64 v[2:3], v[2:3], 0, v[92:93]
	s_mov_b64 s[26:27], 0x1000
	v_or_b32_e32 v1, 1, v0
	s_movk_i32 s7, 0x1000
	v_lshl_add_u64 v[16:17], v[2:3], 0, s[26:27]
	v_mad_i64_i32 v[4:5], s[2:3], v1, s6, v[14:15]
	v_add_co_u32_e32 v2, vcc, s7, v2
	v_lshl_add_u64 v[4:5], v[4:5], 0, s[4:5]
	v_or_b32_e32 v1, 2, v0
	v_addc_co_u32_e32 v3, vcc, 0, v3, vcc
	s_waitcnt lgkmcnt(0)
	s_barrier
	global_load_dword v201, v[88:89], off
	global_load_dword v202, v[88:89], off offset:256
	global_load_dword v203, v[88:89], off offset:512
	global_load_dword v204, v[88:89], off offset:768
	v_lshl_add_u64 v[12:13], v[4:5], 0, v[92:93]
	v_mad_i64_i32 v[4:5], s[2:3], v1, s6, v[14:15]
	global_load_ushort v1, v[2:3], off
	v_lshl_add_u64 v[4:5], v[4:5], 0, s[4:5]
	v_lshl_add_u64 v[8:9], v[4:5], 0, v[92:93]
	ds_read2st64_b32 v[4:5], v108 offset1:1
	ds_read2st64_b32 v[2:3], v108 offset0:2 offset1:3
	global_load_dword v31, v[88:89], off
	v_or_b32_e32 v18, 3, v0
	v_mad_i64_i32 v[20:21], s[2:3], v18, s6, v[14:15]
	v_and_b32_e32 v18, 64, v191
	v_add_u32_e32 v30, 64, v18
	s_waitcnt lgkmcnt(1)
	v_pk_mul_f32 v[18:19], v[4:5], v[4:5]
	s_waitcnt lgkmcnt(0)
	v_pk_mul_f32 v[22:23], v[2:3], v[2:3]
	v_add_f32_e32 v18, v18, v19
	v_add_f32_e32 v18, v18, v22
	v_add_f32_e32 v19, v18, v23
	v_xor_b32_e32 v18, 32, v191
	v_cmp_lt_i32_e32 vcc, v18, v30
	v_lshl_add_u64 v[20:21], v[20:21], 0, s[4:5]
	v_lshl_add_u64 v[24:25], v[20:21], 0, v[92:93]
	v_cndmask_b32_e32 v18, v191, v18, vcc
	v_lshlrev_b32_e32 v18, 2, v18
	ds_bpermute_b32 v22, v18, v19
	v_or_b32_e32 v20, 4, v0
	v_mad_i64_i32 v[20:21], s[2:3], v20, s6, v[14:15]
	v_lshl_add_u64 v[20:21], v[20:21], 0, s[4:5]
	s_waitcnt lgkmcnt(0)
	v_add_f32_e32 v22, v19, v22
	v_xor_b32_e32 v19, 16, v191
	v_cmp_lt_i32_e32 vcc, v19, v30
	v_lshl_add_u64 v[40:41], v[20:21], 0, v[92:93]
	v_xor_b32_e32 v20, 8, v191
	v_cndmask_b32_e32 v19, v191, v19, vcc
	v_lshlrev_b32_e32 v19, 2, v19
	ds_bpermute_b32 v23, v19, v22
	v_cmp_lt_i32_e32 vcc, v20, v30
	v_lshl_add_u64 v[10:11], v[12:13], 0, s[26:27]
	v_lshl_add_u64 v[6:7], v[8:9], 0, s[26:27]
	v_cndmask_b32_e32 v20, v191, v20, vcc
	s_waitcnt lgkmcnt(0)
	v_add_f32_e32 v21, v22, v23
	v_lshlrev_b32_e32 v20, 2, v20
	ds_bpermute_b32 v22, v20, v21
	v_or_b32_e32 v23, 5, v0
	v_mad_i64_i32 v[28:29], s[2:3], v23, s6, v[14:15]
	v_lshl_add_u64 v[28:29], v[28:29], 0, s[4:5]
	s_waitcnt lgkmcnt(0)
	v_add_f32_e32 v21, v21, v22
	v_xor_b32_e32 v22, 4, v191
	v_cmp_lt_i32_e32 vcc, v22, v30
	v_lshl_add_u64 v[44:45], v[28:29], 0, v[92:93]
	v_or_b32_e32 v28, 6, v0
	v_cndmask_b32_e32 v22, v191, v22, vcc
	v_lshlrev_b32_e32 v22, 2, v22
	ds_bpermute_b32 v23, v22, v21
	v_mad_i64_i32 v[28:29], s[2:3], v28, s6, v[14:15]
	v_lshl_add_u64 v[28:29], v[28:29], 0, s[4:5]
	v_lshl_add_u64 v[48:49], v[28:29], 0, v[92:93]
	s_waitcnt lgkmcnt(0)
	v_add_f32_e32 v21, v21, v23
	v_xor_b32_e32 v23, 2, v191
	v_cmp_lt_i32_e32 vcc, v23, v30
	global_load_ushort v54, v[16:17], off offset:128
	global_load_ushort v55, v[16:17], off offset:256
	global_load_ushort v56, v[16:17], off offset:384
	v_cndmask_b32_e32 v23, v191, v23, vcc
	v_lshlrev_b32_e32 v23, 2, v23
	ds_bpermute_b32 v32, v23, v21
	v_lshl_add_u64 v[26:27], v[24:25], 0, s[26:27]
	v_lshl_add_u64 v[42:43], v[40:41], 0, s[26:27]
	v_lshl_add_u64 v[46:47], v[44:45], 0, s[26:27]
	v_lshl_add_u64 v[50:51], v[48:49], 0, s[26:27]
	s_waitcnt lgkmcnt(0)
	v_add_f32_e32 v28, v21, v32
	v_xor_b32_e32 v21, 1, v191
	v_cmp_lt_i32_e32 vcc, v21, v30
	v_or_b32_e32 v30, 7, v0
	v_mad_i64_i32 v[14:15], s[2:3], v30, s6, v[14:15]
	v_cndmask_b32_e32 v21, v191, v21, vcc
	v_lshlrev_b32_e32 v21, 2, v21
	ds_bpermute_b32 v29, v21, v28
	v_lshl_add_u64 v[14:15], v[14:15], 0, s[4:5]
	v_lshl_add_u64 v[52:53], v[14:15], 0, v[92:93]
	v_lshl_add_u64 v[14:15], v[52:53], 0, s[26:27]
	s_waitcnt vmcnt(4)
	v_lshlrev_b32_e32 v1, 16, v1
	s_waitcnt lgkmcnt(0)
; __device__ __forceinline__ bf16_t f2bf(float f) { return (bf16_t)(pk2(f, 0.f) & 0xffffu); }
; __device__ __forceinline__ float bf2f(bf16_t v) { return __uint_as_float(((unsigned)v) << 16); }
; __device__ __forceinline__ float siluf_(float x) { return x * sigmoidf_(x); }
; __device__ __forceinline__ void gla_c3(const Args& a, int l, unsigned char* sm, const bf16_t* __restrict__ PC, const bf16_t* __restrict__ PLR, const bf16_t* __restrict__ UPD, bf16_t* __restrict__ OC) {
;     ...
;             for (int q = 0; q < 4; ++q) rgv[rr][q] = PC[(size_t)(t0 + 8 * wid + rr) * 3072 + 2048 + hd * 256 + lane + 64 * q];
; #pragma unroll
;         for (int rr = 0; rr < 8; ++rr) {
;             const int i = 8 * wid + rr, t = t0 + i;
;             float v[4]; float ss = 0.f;
; #pragma unroll
;             for (int q = 0; q < 4; ++q) { v[q] = Of[i * 260 + lane + 64 * q]; ss += v[q] * v[q]; }
; #pragma unroll
;             for (int o = 32; o >= 1; o >>= 1) ss += __shfl_xor(ss, o);
;             const float sc = rsqrtf(ss * (1.f / 256.f) + EPS_);
; #pragma unroll
;             for (int q = 0; q < 4; ++q) {
;                 const int col = lane + 64 * q;
;                 const float rg = bf2f(rgv[rr][q]);
;                 OC[(size_t)t * 1024 + hd * 256 + col] = f2bf(v[q] * sc * gn[col] * siluf_(rg));
;             }
	v_add_f32_e32 v28, v28, v29
	v_fmamk_f32 v28, v28, 0x3b800000, v188
	v_cmp_gt_f32_e32 vcc, s24, v28
	v_mul_f32_e32 v29, 0x4b800000, v28
	v_readlane_b32 s2, v246, 57
	v_cndmask_b32_e32 v28, v28, v29, vcc
	v_rsq_f32_e32 v28, v28
	v_mul_f32_e32 v29, 0xbfb8aa3b, v1
	v_exp_f32_e32 v29, v29
	v_readlane_b32 s3, v246, 58
	v_mul_f32_e32 v30, 0x45800000, v28
	v_cndmask_b32_e32 v39, v28, v30, vcc
	v_add_co_u32_e32 v12, vcc, s7, v12
	v_add_f32_e32 v29, 1.0, v29
	s_nop 0
	v_addc_co_u32_e32 v13, vcc, 0, v13, vcc
	v_rcp_f32_e32 v29, v29
	v_add_co_u32_e32 v8, vcc, s7, v8
	global_load_ushort v57, v[12:13], off
	global_load_ushort v58, v[10:11], off offset:128
	global_load_ushort v38, v[10:11], off offset:256
	global_load_ushort v37, v[10:11], off offset:384
	v_addc_co_u32_e32 v9, vcc, 0, v9, vcc
	global_load_ushort v36, v[8:9], off
	global_load_ushort v35, v[6:7], off offset:128
	global_load_ushort v34, v[6:7], off offset:256
	global_load_ushort v33, v[6:7], off offset:384
	v_add_co_u32_e32 v6, vcc, s7, v24
	v_mul_f32_e32 v4, v4, v39
	s_nop 0
	v_addc_co_u32_e32 v7, vcc, 0, v25, vcc
	s_waitcnt vmcnt(11)
	v_mul_f32_e32 v4, v31, v4
	v_mul_f32_e32 v1, v29, v1
	global_load_ushort v32, v[6:7], off
	global_load_ushort v31, v[26:27], off offset:128
	global_load_ushort v30, v[26:27], off offset:256
	global_load_ushort v29, v[26:27], off offset:384
	v_add_co_u32_e32 v6, vcc, s7, v40
	v_mul_f32_e32 v1, v1, v4
	s_nop 0
	v_addc_co_u32_e32 v7, vcc, 0, v41, vcc
	global_load_ushort v28, v[6:7], off
	global_load_ushort v27, v[42:43], off offset:128
	global_load_ushort v26, v[42:43], off offset:256
	global_load_ushort v25, v[42:43], off offset:384
	v_add_co_u32_e32 v6, vcc, s7, v44
	s_add_u32 s4, s2, s4
	s_nop 0
	v_addc_co_u32_e32 v7, vcc, 0, v45, vcc
	global_load_ushort v24, v[6:7], off
	global_load_ushort v17, v[46:47], off offset:128
	global_load_ushort v16, v[46:47], off offset:256
	global_load_ushort v13, v[46:47], off offset:384
	v_add_co_u32_e32 v6, vcc, s7, v48
	s_addc_u32 s5, s3, s5
	s_nop 0
	v_addc_co_u32_e32 v7, vcc, 0, v49, vcc
	global_load_ushort v12, v[6:7], off
	global_load_ushort v11, v[50:51], off offset:128
	global_load_ushort v10, v[50:51], off offset:256
	global_load_ushort v9, v[50:51], off offset:384
	v_add_co_u32_e32 v6, vcc, s7, v52
	v_mul_f32_e32 v5, v5, v39
	s_nop 0
	v_addc_co_u32_e32 v7, vcc, 0, v53, vcc
	global_load_ushort v6, v[6:7], off
	s_nop 0
	global_load_ushort v8, v[14:15], off offset:128
	global_load_ushort v7, v[14:15], off offset:256
	global_load_ushort v4, v[14:15], off offset:384
	v_cvt_pk_bf16_f32 v14, v1, v65
	global_load_dword v15, v[88:89], off offset:256
	s_waitcnt vmcnt(31)
	v_lshlrev_b32_e32 v40, 16, v54
	v_mul_f32_e32 v41, 0xbfb8aa3b, v40
	v_exp_f32_e32 v41, v41
	v_ashrrev_i32_e32 v1, 31, v0
	v_lshlrev_b64 v[0:1], 11, v[0:1]
	v_lshl_add_u64 v[0:1], s[4:5], 0, v[0:1]
	v_add_f32_e32 v41, 1.0, v41
	v_rcp_f32_e32 v41, v41
	v_lshl_add_u64 v[0:1], v[0:1], 0, v[92:93]
	global_store_short v[0:1], v14, off
	v_mul_f32_e32 v2, v2, v39
	v_mul_f32_e32 v14, v41, v40
	v_mul_f32_e32 v3, v3, v39
	s_add_i32 s20, s20, s16
	s_cmpk_gt_i32 s20, 0x3ff
	s_waitcnt vmcnt(27)
	v_lshlrev_b32_e32 v38, 16, v38
	s_waitcnt vmcnt(25)
	v_lshlrev_b32_e32 v36, 16, v36
	s_waitcnt vmcnt(24)
	v_lshlrev_b32_e32 v35, 16, v35
	s_waitcnt vmcnt(23)
	v_lshlrev_b32_e32 v34, 16, v34
	s_waitcnt vmcnt(21)
	v_lshlrev_b32_e32 v32, 16, v32
	s_waitcnt vmcnt(20)
	v_lshlrev_b32_e32 v31, 16, v31
	s_waitcnt vmcnt(19)
	v_lshlrev_b32_e32 v30, 16, v30
	s_waitcnt vmcnt(17)
	v_lshlrev_b32_e32 v28, 16, v28
	s_waitcnt vmcnt(16)
	v_lshlrev_b32_e32 v27, 16, v27
	s_waitcnt vmcnt(15)
	v_lshlrev_b32_e32 v26, 16, v26
	s_waitcnt vmcnt(13)
	v_lshlrev_b32_e32 v24, 16, v24
	s_waitcnt vmcnt(12)
	v_lshlrev_b32_e32 v17, 16, v17
	s_waitcnt vmcnt(11)
	v_lshlrev_b32_e32 v16, 16, v16
	s_waitcnt vmcnt(10)
	v_lshlrev_b32_e32 v13, 16, v13
	s_waitcnt vmcnt(9)
	v_lshlrev_b32_e32 v12, 16, v12
	s_waitcnt vmcnt(8)
	v_lshlrev_b32_e32 v11, 16, v11
	s_waitcnt vmcnt(7)
	v_lshlrev_b32_e32 v10, 16, v10
	s_waitcnt vmcnt(6)
	v_lshlrev_b32_e32 v9, 16, v9
	s_waitcnt vmcnt(5)
	v_lshlrev_b32_e32 v6, 16, v6
	s_waitcnt vmcnt(4)
	v_lshlrev_b32_e32 v8, 16, v8
	s_waitcnt vmcnt(2)
	v_lshlrev_b32_e32 v4, 16, v4
	s_waitcnt vmcnt(1)
	v_mul_f32_e32 v5, v15, v5
	v_mul_f32_e32 v5, v14, v5
	v_cvt_pk_bf16_f32 v5, v5, v65
	v_mov_b32_e32 v14, v203
	v_lshlrev_b32_e32 v15, 16, v55
	v_mul_f32_e32 v40, 0xbfb8aa3b, v15
	v_exp_f32_e32 v40, v40
	global_store_short v[0:1], v5, off offset:128
	v_add_f32_e32 v40, 1.0, v40
	v_rcp_f32_e32 v40, v40
	v_mul_f32_e32 v2, v14, v2
	v_mul_f32_e32 v15, v40, v15
	v_mul_f32_e32 v2, v15, v2
	v_cvt_pk_bf16_f32 v2, v2, v65
	v_mov_b32_e32 v5, v204
	v_lshlrev_b32_e32 v14, 16, v56
	v_mul_f32_e32 v15, 0xbfb8aa3b, v14
	v_exp_f32_e32 v15, v15
	global_store_short v[0:1], v2, off offset:256
	v_add_f32_e32 v15, 1.0, v15
	v_rcp_f32_e32 v15, v15
	v_mul_f32_e32 v2, v5, v3
	v_mul_f32_e32 v14, v15, v14
	v_mul_f32_e32 v2, v14, v2
	v_cvt_pk_bf16_f32 v5, v2, v65
	v_mov_b32_e32 v39, v201
	ds_read2st64_b32 v[2:3], v109 offset1:1
	ds_read2st64_b32 v[14:15], v109 offset0:2 offset1:3
	global_store_short v[0:1], v5, off offset:384
	s_waitcnt lgkmcnt(1)
	v_pk_mul_f32 v[40:41], v[2:3], v[2:3]
	s_waitcnt lgkmcnt(0)
	v_pk_mul_f32 v[42:43], v[14:15], v[14:15]
	v_add_f32_e32 v40, v40, v41
	v_add_f32_e32 v40, v40, v42
	v_add_f32_e32 v40, v40, v43
	ds_bpermute_b32 v41, v18, v40
	v_lshlrev_b32_e32 v42, 16, v57
	v_mul_f32_e32 v43, 0xbfb8aa3b, v42
	v_exp_f32_e32 v43, v43
	s_waitcnt lgkmcnt(0)
	v_add_f32_e32 v40, v40, v41
	ds_bpermute_b32 v41, v19, v40
	v_add_f32_e32 v43, 1.0, v43
	v_rcp_f32_e32 v43, v43
	s_waitcnt lgkmcnt(0)
; __device__ __forceinline__ bf16_t f2bf(float f) { return (bf16_t)(pk2(f, 0.f) & 0xffffu); }
; __device__ __forceinline__ float bf2f(bf16_t v) { return __uint_as_float(((unsigned)v) << 16); }
; __device__ __forceinline__ float siluf_(float x) { return x * sigmoidf_(x); }
; __device__ __forceinline__ void gla_c3(const Args& a, int l, unsigned char* sm, const bf16_t* __restrict__ PC, const bf16_t* __restrict__ PLR, const bf16_t* __restrict__ UPD, bf16_t* __restrict__ OC) {
;     ...
;         for (int rr = 0; rr < 8; ++rr) {
;             const int i = 8 * wid + rr, t = t0 + i;
;             float v[4]; float ss = 0.f;
; #pragma unroll
;             for (int q = 0; q < 4; ++q) { v[q] = Of[i * 260 + lane + 64 * q]; ss += v[q] * v[q]; }
; #pragma unroll
;             for (int o = 32; o >= 1; o >>= 1) ss += __shfl_xor(ss, o);
;             const float sc = rsqrtf(ss * (1.f / 256.f) + EPS_);
; #pragma unroll
;             for (int q = 0; q < 4; ++q) {
;                 const int col = lane + 64 * q;
;                 const float rg = bf2f(rgv[rr][q]);
;                 OC[(size_t)t * 1024 + hd * 256 + col] = f2bf(v[q] * sc * gn[col] * siluf_(rg));
;             }
	v_add_f32_e32 v40, v40, v41
	ds_bpermute_b32 v41, v20, v40
	s_waitcnt lgkmcnt(0)
	v_add_f32_e32 v40, v40, v41
	ds_bpermute_b32 v41, v22, v40
	s_waitcnt lgkmcnt(0)
	v_add_f32_e32 v40, v40, v41
	ds_bpermute_b32 v41, v23, v40
	s_waitcnt lgkmcnt(0)
	v_add_f32_e32 v40, v40, v41
	ds_bpermute_b32 v41, v21, v40
	s_waitcnt lgkmcnt(0)
	v_add_f32_e32 v40, v40, v41
	v_fmamk_f32 v40, v40, 0x3b800000, v188
	v_cmp_gt_f32_e32 vcc, s24, v40
	v_mul_f32_e32 v41, 0x4b800000, v40
	s_nop 0
	v_cndmask_b32_e32 v40, v40, v41, vcc
	v_rsq_f32_e32 v40, v40
	v_mul_f32_e32 v41, v43, v42
	v_mul_f32_e32 v0, 0x45800000, v40
	v_cndmask_b32_e32 v5, v40, v0, vcc
	v_mul_f32_e32 v0, v2, v5
	v_lshlrev_b32_e32 v40, 16, v58
	v_mul_f32_e32 v3, v3, v5
	v_mul_f32_e32 v14, v14, v5
	v_mul_f32_e32 v5, v15, v5
	v_mul_f32_e32 v0, v39, v0
	v_mul_f32_e32 v0, v41, v0
	v_cvt_pk_bf16_f32 v2, v0, v65
	v_mov_b32_e32 v39, v202
	v_mul_f32_e32 v0, 0xbfb8aa3b, v40
	v_exp_f32_e32 v41, v0
	v_add_u32_e32 v0, s44, v96
	v_ashrrev_i32_e32 v1, 31, v0
	v_lshlrev_b64 v[0:1], 11, v[0:1]
	v_add_f32_e32 v41, 1.0, v41
	v_rcp_f32_e32 v41, v41
	v_lshl_add_u64 v[0:1], s[4:5], 0, v[0:1]
	v_lshl_add_u64 v[0:1], v[0:1], 0, v[92:93]
	global_store_short v[0:1], v2, off
	v_mul_f32_e32 v40, v41, v40
	v_mul_f32_e32 v2, v39, v3
	v_mul_f32_e32 v2, v40, v2
	v_cvt_pk_bf16_f32 v2, v2, v65
	v_mov_b32_e32 v3, v203
	v_mul_f32_e32 v39, 0xbfb8aa3b, v38
	v_exp_f32_e32 v39, v39
	global_store_short v[0:1], v2, off offset:128
	v_add_f32_e32 v39, 1.0, v39
	v_rcp_f32_e32 v39, v39
	v_mul_f32_e32 v2, v3, v14
	v_mul_f32_e32 v38, v39, v38
	v_mul_f32_e32 v2, v38, v2
	v_cvt_pk_bf16_f32 v2, v2, v65
	v_mov_b32_e32 v3, v204
	v_lshlrev_b32_e32 v14, 16, v37
	v_mul_f32_e32 v37, 0xbfb8aa3b, v14
	v_exp_f32_e32 v37, v37
	global_store_short v[0:1], v2, off offset:256
	v_add_f32_e32 v37, 1.0, v37
	v_rcp_f32_e32 v37, v37
	v_mul_f32_e32 v2, v3, v5
	v_mul_f32_e32 v14, v37, v14
	v_mul_f32_e32 v2, v14, v2
	v_cvt_pk_bf16_f32 v5, v2, v65
	v_mov_b32_e32 v37, v201
	v_add_u32_e32 v14, 16, v109
	ds_read2st64_b32 v[2:3], v14 offset0:4 offset1:5
	ds_read2st64_b32 v[14:15], v14 offset0:6 offset1:7
	global_store_short v[0:1], v5, off offset:384
	s_waitcnt lgkmcnt(1)
	v_pk_mul_f32 v[38:39], v[2:3], v[2:3]
	s_waitcnt lgkmcnt(0)
	v_pk_mul_f32 v[40:41], v[14:15], v[14:15]
	v_add_f32_e32 v38, v38, v39
	v_add_f32_e32 v38, v38, v40
	v_add_f32_e32 v38, v38, v41
	ds_bpermute_b32 v39, v18, v38
	v_mul_f32_e32 v40, 0xbfb8aa3b, v36
	v_exp_f32_e32 v40, v40
	s_waitcnt lgkmcnt(0)
	v_add_f32_e32 v38, v38, v39
	ds_bpermute_b32 v39, v19, v38
	v_add_f32_e32 v40, 1.0, v40
	v_rcp_f32_e32 v40, v40
	s_waitcnt lgkmcnt(0)
	v_add_f32_e32 v38, v38, v39
	ds_bpermute_b32 v39, v20, v38
	v_mul_f32_e32 v36, v40, v36
	s_waitcnt lgkmcnt(0)
	v_add_f32_e32 v38, v38, v39
	ds_bpermute_b32 v39, v22, v38
	s_waitcnt lgkmcnt(0)
	v_add_f32_e32 v38, v38, v39
	ds_bpermute_b32 v39, v23, v38
	s_waitcnt lgkmcnt(0)
	v_add_f32_e32 v38, v38, v39
	ds_bpermute_b32 v39, v21, v38
	s_waitcnt lgkmcnt(0)
	v_add_f32_e32 v38, v38, v39
	v_fmamk_f32 v38, v38, 0x3b800000, v188
	v_cmp_gt_f32_e32 vcc, s24, v38
	v_mul_f32_e32 v39, 0x4b800000, v38
	s_nop 0
	v_cndmask_b32_e32 v38, v38, v39, vcc
	v_rsq_f32_e32 v38, v38
	s_nop 0
	v_mul_f32_e32 v0, 0x45800000, v38
	v_cndmask_b32_e32 v5, v38, v0, vcc
	v_mul_f32_e32 v0, v2, v5
	v_mul_f32_e32 v3, v3, v5
	v_mul_f32_e32 v14, v14, v5
	v_mul_f32_e32 v5, v15, v5
	v_mul_f32_e32 v0, v37, v0
	v_mul_f32_e32 v0, v36, v0
	v_cvt_pk_bf16_f32 v2, v0, v65
	v_mov_b32_e32 v36, v202
	v_mul_f32_e32 v0, 0xbfb8aa3b, v35
	v_exp_f32_e32 v37, v0
	v_add_u32_e32 v0, s44, v97
	v_ashrrev_i32_e32 v1, 31, v0
	v_lshlrev_b64 v[0:1], 11, v[0:1]
	v_add_f32_e32 v37, 1.0, v37
	v_rcp_f32_e32 v37, v37
	v_lshl_add_u64 v[0:1], s[4:5], 0, v[0:1]
	v_lshl_add_u64 v[0:1], v[0:1], 0, v[92:93]
	global_store_short v[0:1], v2, off
	v_mul_f32_e32 v35, v37, v35
	v_mul_f32_e32 v2, v36, v3
	v_mul_f32_e32 v2, v35, v2
	v_cvt_pk_bf16_f32 v2, v2, v65
	v_mov_b32_e32 v3, v203
	v_mul_f32_e32 v35, 0xbfb8aa3b, v34
	v_exp_f32_e32 v35, v35
	global_store_short v[0:1], v2, off offset:128
	v_add_f32_e32 v35, 1.0, v35
	v_rcp_f32_e32 v35, v35
	v_mul_f32_e32 v2, v3, v14
	v_mul_f32_e32 v34, v35, v34
	v_mul_f32_e32 v2, v34, v2
	v_cvt_pk_bf16_f32 v2, v2, v65
	v_mov_b32_e32 v3, v204
	v_lshlrev_b32_e32 v14, 16, v33
	v_mul_f32_e32 v33, 0xbfb8aa3b, v14
	v_exp_f32_e32 v33, v33
	global_store_short v[0:1], v2, off offset:256
	v_add_f32_e32 v33, 1.0, v33
	v_rcp_f32_e32 v33, v33
	v_mul_f32_e32 v2, v3, v5
	v_mul_f32_e32 v14, v33, v14
	v_mul_f32_e32 v2, v14, v2
	v_cvt_pk_bf16_f32 v5, v2, v65
	v_mov_b32_e32 v33, v201
	v_add_u32_e32 v14, 32, v109
	ds_read2st64_b32 v[2:3], v14 offset0:8 offset1:9
	ds_read2st64_b32 v[14:15], v14 offset0:10 offset1:11
	global_store_short v[0:1], v5, off offset:384
	s_waitcnt lgkmcnt(1)
	v_pk_mul_f32 v[34:35], v[2:3], v[2:3]
	s_waitcnt lgkmcnt(0)
	v_pk_mul_f32 v[36:37], v[14:15], v[14:15]
	v_add_f32_e32 v34, v34, v35
	v_add_f32_e32 v34, v34, v36
	v_add_f32_e32 v34, v34, v37
	ds_bpermute_b32 v35, v18, v34
	v_mul_f32_e32 v36, 0xbfb8aa3b, v32
	v_exp_f32_e32 v36, v36
	s_waitcnt lgkmcnt(0)
	v_add_f32_e32 v34, v34, v35
	ds_bpermute_b32 v35, v19, v34
	v_add_f32_e32 v36, 1.0, v36
	v_rcp_f32_e32 v36, v36
	s_waitcnt lgkmcnt(0)
	v_add_f32_e32 v34, v34, v35
	ds_bpermute_b32 v35, v20, v34
	v_mul_f32_e32 v32, v36, v32
	s_waitcnt lgkmcnt(0)
	v_add_f32_e32 v34, v34, v35
	ds_bpermute_b32 v35, v22, v34
	s_waitcnt lgkmcnt(0)
	v_add_f32_e32 v34, v34, v35
	ds_bpermute_b32 v35, v23, v34
	s_waitcnt lgkmcnt(0)
	v_add_f32_e32 v34, v34, v35
	ds_bpermute_b32 v35, v21, v34
	s_waitcnt lgkmcnt(0)
; __device__ __forceinline__ bf16_t f2bf(float f) { return (bf16_t)(pk2(f, 0.f) & 0xffffu); }
; __device__ __forceinline__ float bf2f(bf16_t v) { return __uint_as_float(((unsigned)v) << 16); }
; __device__ __forceinline__ float siluf_(float x) { return x * sigmoidf_(x); }
; __device__ __forceinline__ void gla_c3(const Args& a, int l, unsigned char* sm, const bf16_t* __restrict__ PC, const bf16_t* __restrict__ PLR, const bf16_t* __restrict__ UPD, bf16_t* __restrict__ OC) {
;     ...
;         for (int rr = 0; rr < 8; ++rr) {
;             const int i = 8 * wid + rr, t = t0 + i;
;             float v[4]; float ss = 0.f;
; #pragma unroll
;             for (int q = 0; q < 4; ++q) { v[q] = Of[i * 260 + lane + 64 * q]; ss += v[q] * v[q]; }
; #pragma unroll
;             for (int o = 32; o >= 1; o >>= 1) ss += __shfl_xor(ss, o);
;             const float sc = rsqrtf(ss * (1.f / 256.f) + EPS_);
; #pragma unroll
;             for (int q = 0; q < 4; ++q) {
;                 const int col = lane + 64 * q;
;                 const float rg = bf2f(rgv[rr][q]);
;                 OC[(size_t)t * 1024 + hd * 256 + col] = f2bf(v[q] * sc * gn[col] * siluf_(rg));
;             }
	v_add_f32_e32 v34, v34, v35
	v_fmamk_f32 v34, v34, 0x3b800000, v188
	v_cmp_gt_f32_e32 vcc, s24, v34
	v_mul_f32_e32 v35, 0x4b800000, v34
	s_nop 0
	v_cndmask_b32_e32 v34, v34, v35, vcc
	v_rsq_f32_e32 v34, v34
	s_nop 0
	v_mul_f32_e32 v0, 0x45800000, v34
	v_cndmask_b32_e32 v5, v34, v0, vcc
	v_mul_f32_e32 v0, v2, v5
	v_mul_f32_e32 v3, v3, v5
	v_mul_f32_e32 v14, v14, v5
	v_mul_f32_e32 v5, v15, v5
	v_mul_f32_e32 v0, v33, v0
	v_mul_f32_e32 v0, v32, v0
	v_cvt_pk_bf16_f32 v2, v0, v65
	v_mov_b32_e32 v32, v202
	v_mul_f32_e32 v0, 0xbfb8aa3b, v31
	v_exp_f32_e32 v33, v0
	v_add_u32_e32 v0, s44, v98
	v_ashrrev_i32_e32 v1, 31, v0
	v_lshlrev_b64 v[0:1], 11, v[0:1]
	v_add_f32_e32 v33, 1.0, v33
	v_rcp_f32_e32 v33, v33
	v_lshl_add_u64 v[0:1], s[4:5], 0, v[0:1]
	v_lshl_add_u64 v[0:1], v[0:1], 0, v[92:93]
	global_store_short v[0:1], v2, off
	v_mul_f32_e32 v31, v33, v31
	v_mul_f32_e32 v2, v32, v3
	v_mul_f32_e32 v2, v31, v2
	v_cvt_pk_bf16_f32 v2, v2, v65
	v_mov_b32_e32 v3, v203
	v_mul_f32_e32 v31, 0xbfb8aa3b, v30
	v_exp_f32_e32 v31, v31
	global_store_short v[0:1], v2, off offset:128
	v_add_f32_e32 v31, 1.0, v31
	v_rcp_f32_e32 v31, v31
	v_mul_f32_e32 v2, v3, v14
	v_mul_f32_e32 v30, v31, v30
	v_mul_f32_e32 v2, v30, v2
	v_cvt_pk_bf16_f32 v2, v2, v65
	v_mov_b32_e32 v3, v204
	v_lshlrev_b32_e32 v14, 16, v29
	v_mul_f32_e32 v29, 0xbfb8aa3b, v14
	v_exp_f32_e32 v29, v29
	global_store_short v[0:1], v2, off offset:256
	v_add_f32_e32 v29, 1.0, v29
	v_rcp_f32_e32 v29, v29
	v_mul_f32_e32 v2, v3, v5
	v_mul_f32_e32 v14, v29, v14
	v_mul_f32_e32 v2, v14, v2
	v_cvt_pk_bf16_f32 v5, v2, v65
	v_mov_b32_e32 v29, v201
	v_add_u32_e32 v14, 48, v109
	ds_read2st64_b32 v[2:3], v14 offset0:12 offset1:13
	ds_read2st64_b32 v[14:15], v14 offset0:14 offset1:15
	global_store_short v[0:1], v5, off offset:384
	s_waitcnt lgkmcnt(1)
	v_pk_mul_f32 v[30:31], v[2:3], v[2:3]
	s_waitcnt lgkmcnt(0)
	v_pk_mul_f32 v[32:33], v[14:15], v[14:15]
	v_add_f32_e32 v30, v30, v31
	v_add_f32_e32 v30, v30, v32
	v_add_f32_e32 v30, v30, v33
	ds_bpermute_b32 v31, v18, v30
	v_mul_f32_e32 v32, 0xbfb8aa3b, v28
	v_exp_f32_e32 v32, v32
	s_waitcnt lgkmcnt(0)
	v_add_f32_e32 v30, v30, v31
	ds_bpermute_b32 v31, v19, v30
	v_add_f32_e32 v32, 1.0, v32
	v_rcp_f32_e32 v32, v32
	s_waitcnt lgkmcnt(0)
	v_add_f32_e32 v30, v30, v31
	ds_bpermute_b32 v31, v20, v30
	v_mul_f32_e32 v28, v32, v28
	s_waitcnt lgkmcnt(0)
	v_add_f32_e32 v30, v30, v31
	ds_bpermute_b32 v31, v22, v30
	s_waitcnt lgkmcnt(0)
	v_add_f32_e32 v30, v30, v31
	ds_bpermute_b32 v31, v23, v30
	s_waitcnt lgkmcnt(0)
	v_add_f32_e32 v30, v30, v31
	ds_bpermute_b32 v31, v21, v30
	s_waitcnt lgkmcnt(0)
	v_add_f32_e32 v30, v30, v31
	v_fmamk_f32 v30, v30, 0x3b800000, v188
	v_cmp_gt_f32_e32 vcc, s24, v30
	v_mul_f32_e32 v31, 0x4b800000, v30
	s_nop 0
	v_cndmask_b32_e32 v30, v30, v31, vcc
	v_rsq_f32_e32 v30, v30
	s_nop 0
	v_mul_f32_e32 v0, 0x45800000, v30
	v_cndmask_b32_e32 v5, v30, v0, vcc
	v_mul_f32_e32 v0, v2, v5
	v_mul_f32_e32 v3, v3, v5
	v_mul_f32_e32 v14, v14, v5
	v_mul_f32_e32 v5, v15, v5
	v_mul_f32_e32 v0, v29, v0
	v_mul_f32_e32 v0, v28, v0
	v_cvt_pk_bf16_f32 v2, v0, v65
	v_mov_b32_e32 v28, v202
	v_mul_f32_e32 v0, 0xbfb8aa3b, v27
	v_exp_f32_e32 v29, v0
	v_add_u32_e32 v0, s44, v99
	v_ashrrev_i32_e32 v1, 31, v0
	v_lshlrev_b64 v[0:1], 11, v[0:1]
	v_add_f32_e32 v29, 1.0, v29
	v_rcp_f32_e32 v29, v29
	v_lshl_add_u64 v[0:1], s[4:5], 0, v[0:1]
	v_lshl_add_u64 v[0:1], v[0:1], 0, v[92:93]
	global_store_short v[0:1], v2, off
	v_mul_f32_e32 v27, v29, v27
	v_mul_f32_e32 v2, v28, v3
	v_mul_f32_e32 v2, v27, v2
	v_cvt_pk_bf16_f32 v2, v2, v65
	v_mov_b32_e32 v3, v203
	v_mul_f32_e32 v27, 0xbfb8aa3b, v26
	v_exp_f32_e32 v27, v27
	global_store_short v[0:1], v2, off offset:128
	v_add_f32_e32 v27, 1.0, v27
	v_rcp_f32_e32 v27, v27
	v_mul_f32_e32 v2, v3, v14
	v_mul_f32_e32 v26, v27, v26
	v_mul_f32_e32 v2, v26, v2
	v_cvt_pk_bf16_f32 v2, v2, v65
	v_mov_b32_e32 v3, v204
	v_lshlrev_b32_e32 v14, 16, v25
	v_mul_f32_e32 v25, 0xbfb8aa3b, v14
	v_exp_f32_e32 v25, v25
	global_store_short v[0:1], v2, off offset:256
	v_add_f32_e32 v25, 1.0, v25
	v_rcp_f32_e32 v25, v25
	v_mul_f32_e32 v2, v3, v5
	v_mul_f32_e32 v14, v25, v14
	v_mul_f32_e32 v2, v14, v2
	v_cvt_pk_bf16_f32 v5, v2, v65
	v_mov_b32_e32 v25, v201
	v_add_u32_e32 v14, 64, v109
	ds_read2st64_b32 v[2:3], v14 offset0:16 offset1:17
	ds_read2st64_b32 v[14:15], v14 offset0:18 offset1:19
	global_store_short v[0:1], v5, off offset:384
	s_waitcnt lgkmcnt(1)
	v_pk_mul_f32 v[26:27], v[2:3], v[2:3]
	s_waitcnt lgkmcnt(0)
	v_pk_mul_f32 v[28:29], v[14:15], v[14:15]
	v_add_f32_e32 v26, v26, v27
	v_add_f32_e32 v26, v26, v28
	v_add_f32_e32 v26, v26, v29
	ds_bpermute_b32 v27, v18, v26
	v_mul_f32_e32 v28, 0xbfb8aa3b, v24
	v_exp_f32_e32 v28, v28
	s_waitcnt lgkmcnt(0)
	v_add_f32_e32 v26, v26, v27
	ds_bpermute_b32 v27, v19, v26
	v_add_f32_e32 v28, 1.0, v28
	v_rcp_f32_e32 v28, v28
	s_waitcnt lgkmcnt(0)
	v_add_f32_e32 v26, v26, v27
	ds_bpermute_b32 v27, v20, v26
	v_mul_f32_e32 v24, v28, v24
	s_waitcnt lgkmcnt(0)
	v_add_f32_e32 v26, v26, v27
	ds_bpermute_b32 v27, v22, v26
	s_waitcnt lgkmcnt(0)
	v_add_f32_e32 v26, v26, v27
	ds_bpermute_b32 v27, v23, v26
	s_waitcnt lgkmcnt(0)
	v_add_f32_e32 v26, v26, v27
	ds_bpermute_b32 v27, v21, v26
	s_waitcnt lgkmcnt(0)
; __device__ __forceinline__ bf16_t f2bf(float f) { return (bf16_t)(pk2(f, 0.f) & 0xffffu); }
; __device__ __forceinline__ float bf2f(bf16_t v) { return __uint_as_float(((unsigned)v) << 16); }
; __device__ __forceinline__ float siluf_(float x) { return x * sigmoidf_(x); }
; __device__ __forceinline__ void gla_c3(const Args& a, int l, unsigned char* sm, const bf16_t* __restrict__ PC, const bf16_t* __restrict__ PLR, const bf16_t* __restrict__ UPD, bf16_t* __restrict__ OC) {
;     ...
;         for (int rr = 0; rr < 8; ++rr) {
;             const int i = 8 * wid + rr, t = t0 + i;
;             float v[4]; float ss = 0.f;
; #pragma unroll
;             for (int q = 0; q < 4; ++q) { v[q] = Of[i * 260 + lane + 64 * q]; ss += v[q] * v[q]; }
; #pragma unroll
;             for (int o = 32; o >= 1; o >>= 1) ss += __shfl_xor(ss, o);
;             const float sc = rsqrtf(ss * (1.f / 256.f) + EPS_);
; #pragma unroll
;             for (int q = 0; q < 4; ++q) {
;                 const int col = lane + 64 * q;
;                 const float rg = bf2f(rgv[rr][q]);
;                 OC[(size_t)t * 1024 + hd * 256 + col] = f2bf(v[q] * sc * gn[col] * siluf_(rg));
;             }
	v_add_f32_e32 v26, v26, v27
	v_fmamk_f32 v26, v26, 0x3b800000, v188
	v_cmp_gt_f32_e32 vcc, s24, v26
	v_mul_f32_e32 v27, 0x4b800000, v26
	s_nop 0
	v_cndmask_b32_e32 v26, v26, v27, vcc
	v_rsq_f32_e32 v26, v26
	s_nop 0
	v_mul_f32_e32 v0, 0x45800000, v26
	v_cndmask_b32_e32 v5, v26, v0, vcc
	v_mul_f32_e32 v0, v2, v5
	v_mul_f32_e32 v3, v3, v5
	v_mul_f32_e32 v14, v14, v5
	v_mul_f32_e32 v5, v15, v5
	v_mul_f32_e32 v0, v25, v0
	v_mul_f32_e32 v0, v24, v0
	v_cvt_pk_bf16_f32 v2, v0, v65
	v_mov_b32_e32 v24, v202
	v_mul_f32_e32 v0, 0xbfb8aa3b, v17
	v_exp_f32_e32 v25, v0
	v_add_u32_e32 v0, s44, v100
	v_ashrrev_i32_e32 v1, 31, v0
	v_lshlrev_b64 v[0:1], 11, v[0:1]
	v_add_f32_e32 v25, 1.0, v25
	v_rcp_f32_e32 v25, v25
	v_lshl_add_u64 v[0:1], s[4:5], 0, v[0:1]
	v_lshl_add_u64 v[0:1], v[0:1], 0, v[92:93]
	global_store_short v[0:1], v2, off
	v_mul_f32_e32 v17, v25, v17
	v_mul_f32_e32 v2, v24, v3
	v_mul_f32_e32 v2, v17, v2
	v_cvt_pk_bf16_f32 v2, v2, v65
	v_mov_b32_e32 v3, v203
	v_mul_f32_e32 v17, 0xbfb8aa3b, v16
	v_exp_f32_e32 v17, v17
	global_store_short v[0:1], v2, off offset:128
	v_add_f32_e32 v17, 1.0, v17
	v_rcp_f32_e32 v17, v17
	v_mul_f32_e32 v2, v3, v14
	v_mul_f32_e32 v16, v17, v16
	v_mul_f32_e32 v2, v16, v2
	v_cvt_pk_bf16_f32 v2, v2, v65
	v_mov_b32_e32 v3, v204
	v_mul_f32_e32 v14, 0xbfb8aa3b, v13
	v_exp_f32_e32 v14, v14
	global_store_short v[0:1], v2, off offset:256
	v_add_f32_e32 v14, 1.0, v14
	v_rcp_f32_e32 v14, v14
	v_mul_f32_e32 v2, v3, v5
	v_mul_f32_e32 v13, v14, v13
	v_mul_f32_e32 v2, v13, v2
	v_cvt_pk_bf16_f32 v5, v2, v65
	v_mov_b32_e32 v13, v201
	v_add_u32_e32 v14, 0x50, v109
	ds_read2st64_b32 v[2:3], v14 offset0:20 offset1:21
	ds_read2st64_b32 v[14:15], v14 offset0:22 offset1:23
	global_store_short v[0:1], v5, off offset:384
	s_waitcnt lgkmcnt(1)
	v_pk_mul_f32 v[16:17], v[2:3], v[2:3]
	s_waitcnt lgkmcnt(0)
	v_pk_mul_f32 v[24:25], v[14:15], v[14:15]
	v_add_f32_e32 v16, v16, v17
	v_add_f32_e32 v16, v16, v24
	v_add_f32_e32 v16, v16, v25
	ds_bpermute_b32 v17, v18, v16
	v_mul_f32_e32 v24, 0xbfb8aa3b, v12
	v_exp_f32_e32 v24, v24
	s_waitcnt lgkmcnt(0)
	v_add_f32_e32 v16, v16, v17
	ds_bpermute_b32 v17, v19, v16
	v_add_f32_e32 v24, 1.0, v24
	v_rcp_f32_e32 v24, v24
	s_waitcnt lgkmcnt(0)
	v_add_f32_e32 v16, v16, v17
	ds_bpermute_b32 v17, v20, v16
	v_mul_f32_e32 v12, v24, v12
	s_waitcnt lgkmcnt(0)
	v_add_f32_e32 v16, v16, v17
	ds_bpermute_b32 v17, v22, v16
	s_waitcnt lgkmcnt(0)
	v_add_f32_e32 v16, v16, v17
	ds_bpermute_b32 v17, v23, v16
	s_waitcnt lgkmcnt(0)
	v_add_f32_e32 v16, v16, v17
	ds_bpermute_b32 v17, v21, v16
	s_waitcnt lgkmcnt(0)
	v_add_f32_e32 v16, v16, v17
	v_fmamk_f32 v16, v16, 0x3b800000, v188
	v_cmp_gt_f32_e32 vcc, s24, v16
	v_mul_f32_e32 v17, 0x4b800000, v16
	s_nop 0
	v_cndmask_b32_e32 v16, v16, v17, vcc
	v_rsq_f32_e32 v16, v16
	s_nop 0
	v_mul_f32_e32 v0, 0x45800000, v16
	v_cndmask_b32_e32 v5, v16, v0, vcc
	v_mul_f32_e32 v0, v2, v5
	v_mul_f32_e32 v3, v3, v5
	v_mul_f32_e32 v0, v13, v0
	v_mul_f32_e32 v0, v12, v0
	v_cvt_pk_bf16_f32 v2, v0, v65
	v_mov_b32_e32 v12, v202
	v_mul_f32_e32 v0, 0xbfb8aa3b, v11
	v_exp_f32_e32 v13, v0
	v_add_u32_e32 v0, s44, v101
	v_ashrrev_i32_e32 v1, 31, v0
	v_lshlrev_b64 v[0:1], 11, v[0:1]
	v_add_f32_e32 v13, 1.0, v13
	v_rcp_f32_e32 v13, v13
	v_lshl_add_u64 v[0:1], s[4:5], 0, v[0:1]
	v_lshl_add_u64 v[0:1], v[0:1], 0, v[92:93]
	global_store_short v[0:1], v2, off
	v_mul_f32_e32 v11, v13, v11
	v_mul_f32_e32 v2, v12, v3
	v_mul_f32_e32 v2, v11, v2
	v_cvt_pk_bf16_f32 v2, v2, v65
	v_mov_b32_e32 v3, v203
	v_mul_f32_e32 v11, 0xbfb8aa3b, v10
	v_exp_f32_e32 v11, v11
	global_store_short v[0:1], v2, off offset:128
	v_add_f32_e32 v11, 1.0, v11
	v_rcp_f32_e32 v11, v11
	s_nop 0
	v_mul_f32_e32 v10, v11, v10
	v_mul_f32_e32 v11, v14, v5
	v_mul_f32_e32 v5, v15, v5
	v_mul_f32_e32 v2, v3, v11
	v_mul_f32_e32 v2, v10, v2
	v_cvt_pk_bf16_f32 v2, v2, v65
	v_mov_b32_e32 v3, v204
	v_mul_f32_e32 v10, 0xbfb8aa3b, v9
	v_exp_f32_e32 v10, v10
	global_store_short v[0:1], v2, off offset:256
	v_add_f32_e32 v10, 1.0, v10
	v_rcp_f32_e32 v10, v10
	v_mul_f32_e32 v2, v3, v5
	v_mul_f32_e32 v9, v10, v9
	v_mul_f32_e32 v2, v9, v2
	v_cvt_pk_bf16_f32 v5, v2, v65
	v_mov_b32_e32 v9, v201
	v_add_u32_e32 v10, 0x60, v109
	ds_read2st64_b32 v[2:3], v10 offset0:24 offset1:25
	ds_read2st64_b32 v[10:11], v10 offset0:26 offset1:27
	global_store_short v[0:1], v5, off offset:384
	s_waitcnt lgkmcnt(1)
	v_pk_mul_f32 v[12:13], v[2:3], v[2:3]
	s_waitcnt lgkmcnt(0)
	v_pk_mul_f32 v[14:15], v[10:11], v[10:11]
	v_add_f32_e32 v12, v12, v13
	v_add_f32_e32 v12, v12, v14
	v_add_f32_e32 v12, v12, v15
	ds_bpermute_b32 v13, v18, v12
	v_mul_f32_e32 v14, 0xbfb8aa3b, v6
	v_exp_f32_e32 v14, v14
	s_waitcnt lgkmcnt(0)
	v_add_f32_e32 v12, v12, v13
	ds_bpermute_b32 v13, v19, v12
	v_add_f32_e32 v14, 1.0, v14
	v_rcp_f32_e32 v14, v14
	s_waitcnt lgkmcnt(0)
	v_add_f32_e32 v12, v12, v13
	ds_bpermute_b32 v13, v20, v12
	v_mul_f32_e32 v6, v14, v6
	s_waitcnt lgkmcnt(0)
	v_add_f32_e32 v12, v12, v13
	ds_bpermute_b32 v13, v22, v12
	s_waitcnt lgkmcnt(0)
	v_add_f32_e32 v12, v12, v13
	ds_bpermute_b32 v13, v23, v12
	s_waitcnt lgkmcnt(0)
	v_add_f32_e32 v12, v12, v13
	ds_bpermute_b32 v13, v21, v12
	s_waitcnt lgkmcnt(0)
	v_add_f32_e32 v12, v12, v13
	v_fmamk_f32 v12, v12, 0x3b800000, v188
	v_cmp_gt_f32_e32 vcc, s24, v12
	v_mul_f32_e32 v13, 0x4b800000, v12
	s_nop 0
	v_cndmask_b32_e32 v12, v12, v13, vcc
	v_rsq_f32_e32 v12, v12
	s_nop 0
	v_mul_f32_e32 v0, 0x45800000, v12
	v_cndmask_b32_e32 v5, v12, v0, vcc
	v_mul_f32_e32 v0, v2, v5
	v_mul_f32_e32 v3, v3, v5
	v_mul_f32_e32 v0, v9, v0
	v_mul_f32_e32 v0, v6, v0
	v_cvt_pk_bf16_f32 v2, v0, v65
	v_mov_b32_e32 v6, v202
	v_mul_f32_e32 v0, 0xbfb8aa3b, v8
	v_exp_f32_e32 v9, v0
	v_add_u32_e32 v0, s44, v102
	v_ashrrev_i32_e32 v1, 31, v0
	v_lshlrev_b64 v[0:1], 11, v[0:1]
	v_add_f32_e32 v9, 1.0, v9
	v_rcp_f32_e32 v9, v9
	v_lshl_add_u64 v[0:1], s[4:5], 0, v[0:1]
	v_lshl_add_u64 v[0:1], v[0:1], 0, v[92:93]
	global_store_short v[0:1], v2, off
	v_mul_f32_e32 v8, v9, v8
	v_mul_f32_e32 v2, v6, v3
	v_mul_f32_e32 v2, v8, v2
	v_cvt_pk_bf16_f32 v2, v2, v65
	v_mov_b32_e32 v3, v203
	v_lshlrev_b32_e32 v6, 16, v7
	v_mul_f32_e32 v7, 0xbfb8aa3b, v6
	v_exp_f32_e32 v7, v7
	global_store_short v[0:1], v2, off offset:128
	v_add_f32_e32 v7, 1.0, v7
	v_rcp_f32_e32 v7, v7
	s_nop 0
	v_mul_f32_e32 v6, v7, v6
	v_mul_f32_e32 v7, v10, v5
	v_mul_f32_e32 v5, v11, v5
	v_mul_f32_e32 v2, v3, v7
	v_mul_f32_e32 v2, v6, v2
	v_cvt_pk_bf16_f32 v2, v2, v65
	v_mov_b32_e32 v3, v204
	v_mul_f32_e32 v6, 0xbfb8aa3b, v4
	v_exp_f32_e32 v6, v6
	global_store_short v[0:1], v2, off offset:256
	v_add_f32_e32 v6, 1.0, v6
	v_rcp_f32_e32 v6, v6
	v_mul_f32_e32 v2, v3, v5
	v_mul_f32_e32 v4, v6, v4
	v_mul_f32_e32 v2, v4, v2
	v_cvt_pk_bf16_f32 v2, v2, v65
	global_store_short v[0:1], v2, off offset:384
	s_barrier
	s_cbranch_scc1 .LBB0_480

; __device__ __forceinline__ float bf2f(bf16_t v) { return __uint_as_float(((unsigned)v) << 16); }
; __device__ __forceinline__ int ltid() { int t = threadIdx.x; asm volatile("" : "+v"(t)); return t; }
; __device__ __forceinline__ void gla_b(const Args& a, int l, int hd, int dir, int t0, unsigned char* sm, const bf16_t* __restrict__ PLR) {
;     float* Gb = (float*)(sm + G_GB); float* W2s = (float*)(sm + G_W2); float* Bs = (float*)(sm + G_BS); float* lrs = (float*)(sm + G_LR); float* tot = (float*)(sm + G_TOT);
;     const int tid = ltid();
;     const float* w2 = a.in[18] + ((size_t)(l * 2 + dir) * 16) * 512 + hd * 128;
;     for (int i = tid; i < 2048; i += 512) W2s[i] = w2[(i >> 7) * 512 + (i & 127)];
;     if (tid < 128) Bs[tid] = a.in[19][(l * 2 + dir) * 512 + hd * 128 + tid];
;     for (int i = tid; i < 1024; i += 512) { const int j = i >> 4, r = i & 15; lrs[i] = bf2f(PLR[(size_t)(t0 + j) * 256 + dir * 16 + r]); }
;     __syncthreads();
;     const int d = tid & 127, q = tid >> 7;
;     float run = 0.f;
;     for (int k = 0; k < 16; ++k) {
;         const int s = q * 16 + k, j = dir ? 63 - s : s;
;         float x = Bs[d];
; #pragma unroll
;         for (int r = 0; r < 16; ++r) x += lrs[j * 16 + r] * W2s[r * 128 + d];
;         const float g = (fminf(x, 0.f) - __logf(1.f + __expf(-fabsf(x)))) * (1.f / 16.f);
;         run += g; Gb[j * 129 + d] = run;
;     }
; __device__ __forceinline__ void gla_c3(const Args& a, int l, unsigned char* sm, const bf16_t* __restrict__ PC, const bf16_t* __restrict__ PLR, const bf16_t* __restrict__ UPD, bf16_t* __restrict__ OC) {
;     ...
;             const bf16_t* Sg = UPD + ((size_t)((dir * 4 + hd) * 256 + n)) * 32768;
;             bf16x8 sfr[8];
; #pragma unroll
;             for (int ks = 0; ks < 8; ++ks) sfr[ks] = *(const bf16x8*)(Sg + (32 * wid + r) * 128 + ks * 16 + 8 * h);
.LBB0_456:
	v_readlane_b32 s2, v246, 35
	v_readlane_b32 s6, v247, 3
	v_readlane_b32 s7, v247, 4
	v_readlane_b32 s34, v246, 13
	v_readlane_b32 s35, v246, 14
	s_nop 3
	s_or_b32 s4, s47, s2
	s_lshl_b32 s2, s4, 15
	s_add_u32 s30, s27, s2
	s_addc_u32 s31, s45, 0
	s_lshl_b32 s2, s4, 9
	s_add_i32 s2, s2, s26
	s_lshl_b32 s2, s2, 2
	s_add_u32 s6, s6, s2
	s_addc_u32 s7, s7, 0
	s_lshl_b32 s2, s47, 5
	s_add_u32 s34, s34, s2
	s_addc_u32 s35, s35, 0
	s_lshl_b32 s2, s44, 9
	s_add_u32 s34, s34, s2
	s_addc_u32 s35, s35, 0
	v_and_b32_e32 v32, 0x7f, v171
	v_lshlrev_b32_e32 v32, 2, v32
	v_lshlrev_b32_e32 v33, 2, v171
	v_lshrrev_b32_e32 v34, 4, v171
	v_lshlrev_b32_e32 v34, 9, v34
	v_and_b32_e32 v35, 15, v171
	v_lshl_or_b32 v34, v35, 1, v34
	v_add_u32_e32 v35, 0x4000, v34
	global_load_ushort v36, v34, s[34:35]
	global_load_ushort v37, v35, s[34:35]
	global_load_dword v38, v32, s[6:7]
	global_load_dword v201, v32, s[30:31]
	global_load_dword v202, v32, s[30:31] offset:2048
	s_add_u32 s30, s30, 0x1000
	s_addc_u32 s31, s31, 0
	global_load_dword v203, v32, s[30:31]
	global_load_dword v204, v32, s[30:31] offset:2048
	s_add_u32 s30, s30, 0x1000
	s_addc_u32 s31, s31, 0
	global_load_dword v205, v32, s[30:31]
	global_load_dword v206, v32, s[30:31] offset:2048
	s_add_u32 s30, s30, 0x1000
	s_addc_u32 s31, s31, 0
	global_load_dword v207, v32, s[30:31]
	global_load_dword v208, v32, s[30:31] offset:2048
	s_add_u32 s30, s30, 0x1000
	s_addc_u32 s31, s31, 0
	global_load_dword v209, v32, s[30:31]
	global_load_dword v210, v32, s[30:31] offset:2048
	s_add_u32 s30, s30, 0x1000
	s_addc_u32 s31, s31, 0
	global_load_dword v211, v32, s[30:31]
	global_load_dword v212, v32, s[30:31] offset:2048
	s_add_u32 s30, s30, 0x1000
	s_addc_u32 s31, s31, 0
	global_load_dword v213, v32, s[30:31]
	global_load_dword v214, v32, s[30:31] offset:2048
	s_add_u32 s30, s30, 0x1000
	s_addc_u32 s31, s31, 0
	global_load_dword v215, v32, s[30:31]
	global_load_dword v216, v32, s[30:31] offset:2048
	s_lshl_b32 s2, s47, 10
	s_add_i32 s2, s2, s20
	s_ashr_i32 s3, s2, 31
	s_lshl_b64 s[2:3], s[2:3], 16
	v_lshl_add_u64 v[160:161], v[82:83], 0, s[2:3]
	global_load_dwordx4 v[78:81], v[160:161], off
	global_load_dwordx4 v[74:77], v[160:161], off offset:32
	global_load_dwordx4 v[70:73], v[160:161], off offset:64
	global_load_dwordx4 v[66:69], v[160:161], off offset:96
	global_load_dwordx4 v[60:63], v[160:161], off offset:128
	global_load_dwordx4 v[56:59], v[160:161], off offset:160
	global_load_dwordx4 v[52:55], v[160:161], off offset:192
	global_load_dwordx4 v[48:51], v[160:161], off offset:224
	s_waitcnt vmcnt(25)
	v_lshlrev_b32_e32 v36, 16, v36
	v_lshlrev_b32_e32 v37, 16, v37
	ds_write_b32 v33, v36 offset:41728
	ds_write_b32 v33, v37 offset:43776
	s_waitcnt lgkmcnt(0)
	s_barrier
	v_lshrrev_b32_e32 v39, 7, v171
	v_lshlrev_b32_e32 v39, 4, v39
	v_sub_u32_e32 v40, 63, v39
	s_cmp_eq_u32 s47, 0
	s_cselect_b32 s3, 64, 0xffffffc0
	s_movk_i32 s101, 0x204
	s_cselect_b32 s101, s101, 0xfffffdfc
	v_cndmask_b32_e64 v39, v40, v39, s[28:29]
	v_lshlrev_b32_e32 v143, 6, v39
	v_add_u32_e32 v143, 0xa300, v143
	v_add_u32_e32 v144, s3, v143
	v_mul_u32_u24_e32 v40, 0x204, v39
	v_add_u32_e32 v40, v40, v32
	s_lshl_b32 s100, s3, 1
	ds_read_b128 v[172:175], v143
	ds_read_b128 v[176:179], v143 offset:16
	ds_read_b128 v[180:183], v143 offset:32
	ds_read_b128 v[164:167], v143 offset:48
	ds_read_b128 v[228:231], v144
	ds_read_b128 v[232:235], v144 offset:16
	ds_read_b128 v[236:239], v144 offset:32
	ds_read_b128 v[240:243], v144 offset:48
	s_mov_b32 s2, 0x3d800000
	s_waitcnt vmcnt(8)
	s_waitcnt lgkmcnt(0)
	v_mov_b32_e32 v141, v38
	v_mov_b32_e32 v142, v38
	v_fmac_f32_e32 v141, v172, v201
	v_fmac_f32_e32 v142, v228, v201
	v_fmac_f32_e32 v141, v173, v202
	v_fmac_f32_e32 v142, v229, v202
	v_fmac_f32_e32 v141, v174, v203
	v_fmac_f32_e32 v142, v230, v203
	v_fmac_f32_e32 v141, v175, v204
	v_fmac_f32_e32 v142, v231, v204
	v_fmac_f32_e32 v141, v176, v205
	v_fmac_f32_e32 v142, v232, v205
	v_fmac_f32_e32 v141, v177, v206
	v_fmac_f32_e32 v142, v233, v206
	v_fmac_f32_e32 v141, v178, v207
	v_fmac_f32_e32 v142, v234, v207
	v_fmac_f32_e32 v141, v179, v208
	v_fmac_f32_e32 v142, v235, v208
	v_fmac_f32_e32 v141, v180, v209
	v_fmac_f32_e32 v142, v236, v209
	v_fmac_f32_e32 v141, v181, v210
	v_fmac_f32_e32 v142, v237, v210
	v_fmac_f32_e32 v141, v182, v211
	v_fmac_f32_e32 v142, v238, v211
	v_fmac_f32_e32 v141, v183, v212
	v_fmac_f32_e32 v142, v239, v212
	v_fmac_f32_e32 v141, v164, v213
	v_fmac_f32_e32 v142, v240, v213
	v_fmac_f32_e32 v141, v165, v214
	v_fmac_f32_e32 v142, v241, v214
	v_fmac_f32_e32 v141, v166, v215
	v_fmac_f32_e32 v142, v242, v215
	v_fmac_f32_e32 v141, v167, v216
	v_fmac_f32_e32 v142, v243, v216
	v_add_u32_e32 v143, s100, v143
	v_add_u32_e32 v144, s100, v144
	ds_read_b128 v[172:175], v143
	ds_read_b128 v[176:179], v143 offset:16
	ds_read_b128 v[180:183], v143 offset:32
	ds_read_b128 v[164:167], v143 offset:48
	ds_read_b128 v[228:231], v144
	ds_read_b128 v[232:235], v144 offset:16
	ds_read_b128 v[236:239], v144 offset:32
	ds_read_b128 v[240:243], v144 offset:48
	v_mul_f32_e64 v41, |v141|, s61
	v_mul_f32_e64 v42, |v142|, s61
	v_exp_f32_e32 v41, v41
	v_exp_f32_e32 v42, v42
	v_min_f32_e32 v43, 0, v141
	v_min_f32_e32 v44, 0, v142
	v_add_f32_e32 v41, 1.0, v41
	v_add_f32_e32 v42, 1.0, v42
	v_cmp_gt_f32_e64 s[4:5], s24, v41
	v_cmp_gt_f32_e64 s[6:7], s24, v42
	s_nop 1
	v_cndmask_b32_e64 v45, 0, 32, s[4:5]
	v_cndmask_b32_e64 v46, 0, 32, s[6:7]
	v_ldexp_f32 v41, v41, v45
	v_ldexp_f32 v42, v42, v46
	v_log_f32_e32 v41, v41
	v_log_f32_e32 v42, v42
	v_cndmask_b32_e64 v45, 0, v192, s[4:5]
	v_cndmask_b32_e64 v46, 0, v192, s[6:7]
	v_mul_f32_e32 v47, 0x3f317217, v41
	v_mul_f32_e32 v140, 0x3f317217, v42
	v_fma_f32 v47, v41, s62, -v47
	v_fma_f32 v140, v42, s62, -v140
	v_fmac_f32_e32 v47, 0x3377d1cf, v41
	v_fmac_f32_e32 v140, 0x3377d1cf, v42
	v_fmac_f32_e32 v47, 0x3f317217, v41
	v_fmac_f32_e32 v140, 0x3f317217, v42
	v_cmp_lt_f32_e64 s[30:31], |v41|, s63
	v_cmp_lt_f32_e64 s[34:35], |v42|, s63
	s_nop 1
	v_cndmask_b32_e64 v41, v41, v47, s[30:31]
	v_cndmask_b32_e64 v42, v42, v140, s[34:35]
	v_sub_f32_e32 v41, v41, v45
	v_sub_f32_e32 v42, v42, v46
	v_sub_f32_e32 v41, v43, v41
	v_sub_f32_e32 v42, v44, v42
	v_fma_f32 v217, v41, s2, v65
	v_fma_f32 v218, v42, s2, v217
	s_waitcnt lgkmcnt(0)
; __device__ __forceinline__ void gla_b(const Args& a, int l, int hd, int dir, int t0, unsigned char* sm, const bf16_t* __restrict__ PLR) {
;     ...
;     for (int k = 0; k < 16; ++k) {
;         const int s = q * 16 + k, j = dir ? 63 - s : s;
;         float x = Bs[d];
; #pragma unroll
;         for (int r = 0; r < 16; ++r) x += lrs[j * 16 + r] * W2s[r * 128 + d];
;         const float g = (fminf(x, 0.f) - __logf(1.f + __expf(-fabsf(x)))) * (1.f / 16.f);
;         run += g; Gb[j * 129 + d] = run;
;     }
	v_mov_b32_e32 v141, v38
	v_mov_b32_e32 v142, v38
	v_fmac_f32_e32 v141, v172, v201
	v_fmac_f32_e32 v142, v228, v201
	v_fmac_f32_e32 v141, v173, v202
	v_fmac_f32_e32 v142, v229, v202
	v_fmac_f32_e32 v141, v174, v203
	v_fmac_f32_e32 v142, v230, v203
	v_fmac_f32_e32 v141, v175, v204
	v_fmac_f32_e32 v142, v231, v204
	v_fmac_f32_e32 v141, v176, v205
	v_fmac_f32_e32 v142, v232, v205
	v_fmac_f32_e32 v141, v177, v206
	v_fmac_f32_e32 v142, v233, v206
	v_fmac_f32_e32 v141, v178, v207
	v_fmac_f32_e32 v142, v234, v207
	v_fmac_f32_e32 v141, v179, v208
	v_fmac_f32_e32 v142, v235, v208
	v_fmac_f32_e32 v141, v180, v209
	v_fmac_f32_e32 v142, v236, v209
	v_fmac_f32_e32 v141, v181, v210
	v_fmac_f32_e32 v142, v237, v210
	v_fmac_f32_e32 v141, v182, v211
	v_fmac_f32_e32 v142, v238, v211
	v_fmac_f32_e32 v141, v183, v212
	v_fmac_f32_e32 v142, v239, v212
	v_fmac_f32_e32 v141, v164, v213
	v_fmac_f32_e32 v142, v240, v213
	v_fmac_f32_e32 v141, v165, v214
	v_fmac_f32_e32 v142, v241, v214
	v_fmac_f32_e32 v141, v166, v215
	v_fmac_f32_e32 v142, v242, v215
	v_fmac_f32_e32 v141, v167, v216
	v_fmac_f32_e32 v142, v243, v216
	v_add_u32_e32 v143, s100, v143
	v_add_u32_e32 v144, s100, v144
	ds_read_b128 v[172:175], v143
	ds_read_b128 v[176:179], v143 offset:16
	ds_read_b128 v[180:183], v143 offset:32
	ds_read_b128 v[164:167], v143 offset:48
	ds_read_b128 v[228:231], v144
	ds_read_b128 v[232:235], v144 offset:16
	ds_read_b128 v[236:239], v144 offset:32
	ds_read_b128 v[240:243], v144 offset:48
	v_mul_f32_e64 v41, |v141|, s61
	v_mul_f32_e64 v42, |v142|, s61
	v_exp_f32_e32 v41, v41
	v_exp_f32_e32 v42, v42
	v_min_f32_e32 v43, 0, v141
	v_min_f32_e32 v44, 0, v142
	v_add_f32_e32 v41, 1.0, v41
	v_add_f32_e32 v42, 1.0, v42
	v_cmp_gt_f32_e64 s[4:5], s24, v41
	v_cmp_gt_f32_e64 s[6:7], s24, v42
	s_nop 1
	v_cndmask_b32_e64 v45, 0, 32, s[4:5]
	v_cndmask_b32_e64 v46, 0, 32, s[6:7]
	v_ldexp_f32 v41, v41, v45
	v_ldexp_f32 v42, v42, v46
	v_log_f32_e32 v41, v41
	v_log_f32_e32 v42, v42
	v_cndmask_b32_e64 v45, 0, v192, s[4:5]
	v_cndmask_b32_e64 v46, 0, v192, s[6:7]
	v_mul_f32_e32 v47, 0x3f317217, v41
	v_mul_f32_e32 v140, 0x3f317217, v42
	v_fma_f32 v47, v41, s62, -v47
	v_fma_f32 v140, v42, s62, -v140
	v_fmac_f32_e32 v47, 0x3377d1cf, v41
	v_fmac_f32_e32 v140, 0x3377d1cf, v42
	v_fmac_f32_e32 v47, 0x3f317217, v41
	v_fmac_f32_e32 v140, 0x3f317217, v42
	v_cmp_lt_f32_e64 s[30:31], |v41|, s63
	v_cmp_lt_f32_e64 s[34:35], |v42|, s63
	s_nop 1
	v_cndmask_b32_e64 v41, v41, v47, s[30:31]
	v_cndmask_b32_e64 v42, v42, v140, s[34:35]
	v_sub_f32_e32 v41, v41, v45
	v_sub_f32_e32 v42, v42, v46
	v_sub_f32_e32 v41, v43, v41
	v_sub_f32_e32 v42, v44, v42
	v_fma_f32 v219, v41, s2, v218
	v_fma_f32 v220, v42, s2, v219
	s_waitcnt lgkmcnt(0)
	v_mov_b32_e32 v141, v38
	v_mov_b32_e32 v142, v38
	v_fmac_f32_e32 v141, v172, v201
	v_fmac_f32_e32 v142, v228, v201
	v_fmac_f32_e32 v141, v173, v202
	v_fmac_f32_e32 v142, v229, v202
	v_fmac_f32_e32 v141, v174, v203
	v_fmac_f32_e32 v142, v230, v203
	v_fmac_f32_e32 v141, v175, v204
	v_fmac_f32_e32 v142, v231, v204
	v_fmac_f32_e32 v141, v176, v205
	v_fmac_f32_e32 v142, v232, v205
	v_fmac_f32_e32 v141, v177, v206
	v_fmac_f32_e32 v142, v233, v206
	v_fmac_f32_e32 v141, v178, v207
	v_fmac_f32_e32 v142, v234, v207
	v_fmac_f32_e32 v141, v179, v208
	v_fmac_f32_e32 v142, v235, v208
	v_fmac_f32_e32 v141, v180, v209
	v_fmac_f32_e32 v142, v236, v209
	v_fmac_f32_e32 v141, v181, v210
	v_fmac_f32_e32 v142, v237, v210
	v_fmac_f32_e32 v141, v182, v211
	v_fmac_f32_e32 v142, v238, v211
	v_fmac_f32_e32 v141, v183, v212
	v_fmac_f32_e32 v142, v239, v212
	v_fmac_f32_e32 v141, v164, v213
	v_fmac_f32_e32 v142, v240, v213
	v_fmac_f32_e32 v141, v165, v214
	v_fmac_f32_e32 v142, v241, v214
	v_fmac_f32_e32 v141, v166, v215
	v_fmac_f32_e32 v142, v242, v215
	v_fmac_f32_e32 v141, v167, v216
	v_fmac_f32_e32 v142, v243, v216
	v_add_u32_e32 v143, s100, v143
	v_add_u32_e32 v144, s100, v144
	ds_read_b128 v[172:175], v143
	ds_read_b128 v[176:179], v143 offset:16
	ds_read_b128 v[180:183], v143 offset:32
	ds_read_b128 v[164:167], v143 offset:48
	ds_read_b128 v[228:231], v144
	ds_read_b128 v[232:235], v144 offset:16
	ds_read_b128 v[236:239], v144 offset:32
	ds_read_b128 v[240:243], v144 offset:48
	v_mul_f32_e64 v41, |v141|, s61
	v_mul_f32_e64 v42, |v142|, s61
	v_exp_f32_e32 v41, v41
	v_exp_f32_e32 v42, v42
	v_min_f32_e32 v43, 0, v141
	v_min_f32_e32 v44, 0, v142
	v_add_f32_e32 v41, 1.0, v41
	v_add_f32_e32 v42, 1.0, v42
	v_cmp_gt_f32_e64 s[4:5], s24, v41
	v_cmp_gt_f32_e64 s[6:7], s24, v42
	s_nop 1
	v_cndmask_b32_e64 v45, 0, 32, s[4:5]
	v_cndmask_b32_e64 v46, 0, 32, s[6:7]
	v_ldexp_f32 v41, v41, v45
	v_ldexp_f32 v42, v42, v46
	v_log_f32_e32 v41, v41
	v_log_f32_e32 v42, v42
	v_cndmask_b32_e64 v45, 0, v192, s[4:5]
	v_cndmask_b32_e64 v46, 0, v192, s[6:7]
	v_mul_f32_e32 v47, 0x3f317217, v41
	v_mul_f32_e32 v140, 0x3f317217, v42
	v_fma_f32 v47, v41, s62, -v47
	v_fma_f32 v140, v42, s62, -v140
	v_fmac_f32_e32 v47, 0x3377d1cf, v41
	v_fmac_f32_e32 v140, 0x3377d1cf, v42
	v_fmac_f32_e32 v47, 0x3f317217, v41
	v_fmac_f32_e32 v140, 0x3f317217, v42
	v_cmp_lt_f32_e64 s[30:31], |v41|, s63
	v_cmp_lt_f32_e64 s[34:35], |v42|, s63
	s_nop 1
	v_cndmask_b32_e64 v41, v41, v47, s[30:31]
	v_cndmask_b32_e64 v42, v42, v140, s[34:35]
	v_sub_f32_e32 v41, v41, v45
	v_sub_f32_e32 v42, v42, v46
	v_sub_f32_e32 v41, v43, v41
	v_sub_f32_e32 v42, v44, v42
	v_fma_f32 v221, v41, s2, v220
	v_fma_f32 v222, v42, s2, v221
	s_waitcnt lgkmcnt(0)
; __device__ __forceinline__ void gla_b(const Args& a, int l, int hd, int dir, int t0, unsigned char* sm, const bf16_t* __restrict__ PLR) {
;     ...
;     for (int k = 0; k < 16; ++k) {
;         const int s = q * 16 + k, j = dir ? 63 - s : s;
;         float x = Bs[d];
; #pragma unroll
;         for (int r = 0; r < 16; ++r) x += lrs[j * 16 + r] * W2s[r * 128 + d];
;         const float g = (fminf(x, 0.f) - __logf(1.f + __expf(-fabsf(x)))) * (1.f / 16.f);
;         run += g; Gb[j * 129 + d] = run;
;     }
	v_mov_b32_e32 v141, v38
	v_mov_b32_e32 v142, v38
	v_fmac_f32_e32 v141, v172, v201
	v_fmac_f32_e32 v142, v228, v201
	v_fmac_f32_e32 v141, v173, v202
	v_fmac_f32_e32 v142, v229, v202
	v_fmac_f32_e32 v141, v174, v203
	v_fmac_f32_e32 v142, v230, v203
	v_fmac_f32_e32 v141, v175, v204
	v_fmac_f32_e32 v142, v231, v204
	v_fmac_f32_e32 v141, v176, v205
	v_fmac_f32_e32 v142, v232, v205
	v_fmac_f32_e32 v141, v177, v206
	v_fmac_f32_e32 v142, v233, v206
	v_fmac_f32_e32 v141, v178, v207
	v_fmac_f32_e32 v142, v234, v207
	v_fmac_f32_e32 v141, v179, v208
	v_fmac_f32_e32 v142, v235, v208
	v_fmac_f32_e32 v141, v180, v209
	v_fmac_f32_e32 v142, v236, v209
	v_fmac_f32_e32 v141, v181, v210
	v_fmac_f32_e32 v142, v237, v210
	v_fmac_f32_e32 v141, v182, v211
	v_fmac_f32_e32 v142, v238, v211
	v_fmac_f32_e32 v141, v183, v212
	v_fmac_f32_e32 v142, v239, v212
	v_fmac_f32_e32 v141, v164, v213
	v_fmac_f32_e32 v142, v240, v213
	v_fmac_f32_e32 v141, v165, v214
	v_fmac_f32_e32 v142, v241, v214
	v_fmac_f32_e32 v141, v166, v215
	v_fmac_f32_e32 v142, v242, v215
	v_fmac_f32_e32 v141, v167, v216
	v_fmac_f32_e32 v142, v243, v216
	v_add_u32_e32 v143, s100, v143
	v_add_u32_e32 v144, s100, v144
	ds_read_b128 v[172:175], v143
	ds_read_b128 v[176:179], v143 offset:16
	ds_read_b128 v[180:183], v143 offset:32
	ds_read_b128 v[164:167], v143 offset:48
	ds_read_b128 v[228:231], v144
	ds_read_b128 v[232:235], v144 offset:16
	ds_read_b128 v[236:239], v144 offset:32
	ds_read_b128 v[240:243], v144 offset:48
	v_mul_f32_e64 v41, |v141|, s61
	v_mul_f32_e64 v42, |v142|, s61
	v_exp_f32_e32 v41, v41
	v_exp_f32_e32 v42, v42
	v_min_f32_e32 v43, 0, v141
	v_min_f32_e32 v44, 0, v142
	v_add_f32_e32 v41, 1.0, v41
	v_add_f32_e32 v42, 1.0, v42
	v_cmp_gt_f32_e64 s[4:5], s24, v41
	v_cmp_gt_f32_e64 s[6:7], s24, v42
	s_nop 1
	v_cndmask_b32_e64 v45, 0, 32, s[4:5]
	v_cndmask_b32_e64 v46, 0, 32, s[6:7]
	v_ldexp_f32 v41, v41, v45
	v_ldexp_f32 v42, v42, v46
	v_log_f32_e32 v41, v41
	v_log_f32_e32 v42, v42
	v_cndmask_b32_e64 v45, 0, v192, s[4:5]
	v_cndmask_b32_e64 v46, 0, v192, s[6:7]
	v_mul_f32_e32 v47, 0x3f317217, v41
	v_mul_f32_e32 v140, 0x3f317217, v42
	v_fma_f32 v47, v41, s62, -v47
	v_fma_f32 v140, v42, s62, -v140
	v_fmac_f32_e32 v47, 0x3377d1cf, v41
	v_fmac_f32_e32 v140, 0x3377d1cf, v42
	v_fmac_f32_e32 v47, 0x3f317217, v41
	v_fmac_f32_e32 v140, 0x3f317217, v42
	v_cmp_lt_f32_e64 s[30:31], |v41|, s63
	v_cmp_lt_f32_e64 s[34:35], |v42|, s63
	s_nop 1
	v_cndmask_b32_e64 v41, v41, v47, s[30:31]
	v_cndmask_b32_e64 v42, v42, v140, s[34:35]
	v_sub_f32_e32 v41, v41, v45
	v_sub_f32_e32 v42, v42, v46
	v_sub_f32_e32 v41, v43, v41
	v_sub_f32_e32 v42, v44, v42
	v_fma_f32 v223, v41, s2, v222
	v_fma_f32 v224, v42, s2, v223
	s_waitcnt lgkmcnt(0)
	v_mov_b32_e32 v141, v38
	v_mov_b32_e32 v142, v38
	v_fmac_f32_e32 v141, v172, v201
	v_fmac_f32_e32 v142, v228, v201
	v_fmac_f32_e32 v141, v173, v202
	v_fmac_f32_e32 v142, v229, v202
	v_fmac_f32_e32 v141, v174, v203
	v_fmac_f32_e32 v142, v230, v203
	v_fmac_f32_e32 v141, v175, v204
	v_fmac_f32_e32 v142, v231, v204
	v_fmac_f32_e32 v141, v176, v205
	v_fmac_f32_e32 v142, v232, v205
	v_fmac_f32_e32 v141, v177, v206
	v_fmac_f32_e32 v142, v233, v206
	v_fmac_f32_e32 v141, v178, v207
	v_fmac_f32_e32 v142, v234, v207
	v_fmac_f32_e32 v141, v179, v208
	v_fmac_f32_e32 v142, v235, v208
	v_fmac_f32_e32 v141, v180, v209
	v_fmac_f32_e32 v142, v236, v209
	v_fmac_f32_e32 v141, v181, v210
	v_fmac_f32_e32 v142, v237, v210
	v_fmac_f32_e32 v141, v182, v211
	v_fmac_f32_e32 v142, v238, v211
	v_fmac_f32_e32 v141, v183, v212
	v_fmac_f32_e32 v142, v239, v212
	v_fmac_f32_e32 v141, v164, v213
	v_fmac_f32_e32 v142, v240, v213
	v_fmac_f32_e32 v141, v165, v214
	v_fmac_f32_e32 v142, v241, v214
	v_fmac_f32_e32 v141, v166, v215
	v_fmac_f32_e32 v142, v242, v215
	v_fmac_f32_e32 v141, v167, v216
	v_fmac_f32_e32 v142, v243, v216
	v_add_u32_e32 v143, s100, v143
	v_add_u32_e32 v144, s100, v144
	ds_read_b128 v[172:175], v143
	ds_read_b128 v[176:179], v143 offset:16
	ds_read_b128 v[180:183], v143 offset:32
	ds_read_b128 v[164:167], v143 offset:48
	ds_read_b128 v[228:231], v144
	ds_read_b128 v[232:235], v144 offset:16
	ds_read_b128 v[236:239], v144 offset:32
	ds_read_b128 v[240:243], v144 offset:48
	v_mul_f32_e64 v41, |v141|, s61
	v_mul_f32_e64 v42, |v142|, s61
	v_exp_f32_e32 v41, v41
	v_exp_f32_e32 v42, v42
	v_min_f32_e32 v43, 0, v141
	v_min_f32_e32 v44, 0, v142
	v_add_f32_e32 v41, 1.0, v41
	v_add_f32_e32 v42, 1.0, v42
	v_cmp_gt_f32_e64 s[4:5], s24, v41
	v_cmp_gt_f32_e64 s[6:7], s24, v42
	s_nop 1
	v_cndmask_b32_e64 v45, 0, 32, s[4:5]
	v_cndmask_b32_e64 v46, 0, 32, s[6:7]
	v_ldexp_f32 v41, v41, v45
	v_ldexp_f32 v42, v42, v46
	v_log_f32_e32 v41, v41
	v_log_f32_e32 v42, v42
	v_cndmask_b32_e64 v45, 0, v192, s[4:5]
	v_cndmask_b32_e64 v46, 0, v192, s[6:7]
	v_mul_f32_e32 v47, 0x3f317217, v41
	v_mul_f32_e32 v140, 0x3f317217, v42
	v_fma_f32 v47, v41, s62, -v47
	v_fma_f32 v140, v42, s62, -v140
	v_fmac_f32_e32 v47, 0x3377d1cf, v41
	v_fmac_f32_e32 v140, 0x3377d1cf, v42
	v_fmac_f32_e32 v47, 0x3f317217, v41
	v_fmac_f32_e32 v140, 0x3f317217, v42
	v_cmp_lt_f32_e64 s[30:31], |v41|, s63
	v_cmp_lt_f32_e64 s[34:35], |v42|, s63
	s_nop 1
	v_cndmask_b32_e64 v41, v41, v47, s[30:31]
	v_cndmask_b32_e64 v42, v42, v140, s[34:35]
	v_sub_f32_e32 v41, v41, v45
	v_sub_f32_e32 v42, v42, v46
	v_sub_f32_e32 v41, v43, v41
	v_sub_f32_e32 v42, v44, v42
	v_fma_f32 v225, v41, s2, v224
	v_fma_f32 v226, v42, s2, v225
	s_waitcnt lgkmcnt(0)
; __device__ __forceinline__ void gla_b(const Args& a, int l, int hd, int dir, int t0, unsigned char* sm, const bf16_t* __restrict__ PLR) {
;     ...
;     for (int k = 0; k < 16; ++k) {
;         const int s = q * 16 + k, j = dir ? 63 - s : s;
;         float x = Bs[d];
; #pragma unroll
;         for (int r = 0; r < 16; ++r) x += lrs[j * 16 + r] * W2s[r * 128 + d];
;         const float g = (fminf(x, 0.f) - __logf(1.f + __expf(-fabsf(x)))) * (1.f / 16.f);
;         run += g; Gb[j * 129 + d] = run;
;     }
	v_mov_b32_e32 v141, v38
	v_mov_b32_e32 v142, v38
	v_fmac_f32_e32 v141, v172, v201
	v_fmac_f32_e32 v142, v228, v201
	v_fmac_f32_e32 v141, v173, v202
	v_fmac_f32_e32 v142, v229, v202
	v_fmac_f32_e32 v141, v174, v203
	v_fmac_f32_e32 v142, v230, v203
	v_fmac_f32_e32 v141, v175, v204
	v_fmac_f32_e32 v142, v231, v204
	v_fmac_f32_e32 v141, v176, v205
	v_fmac_f32_e32 v142, v232, v205
	v_fmac_f32_e32 v141, v177, v206
	v_fmac_f32_e32 v142, v233, v206
	v_fmac_f32_e32 v141, v178, v207
	v_fmac_f32_e32 v142, v234, v207
	v_fmac_f32_e32 v141, v179, v208
	v_fmac_f32_e32 v142, v235, v208
	v_fmac_f32_e32 v141, v180, v209
	v_fmac_f32_e32 v142, v236, v209
	v_fmac_f32_e32 v141, v181, v210
	v_fmac_f32_e32 v142, v237, v210
	v_fmac_f32_e32 v141, v182, v211
	v_fmac_f32_e32 v142, v238, v211
	v_fmac_f32_e32 v141, v183, v212
	v_fmac_f32_e32 v142, v239, v212
	v_fmac_f32_e32 v141, v164, v213
	v_fmac_f32_e32 v142, v240, v213
	v_fmac_f32_e32 v141, v165, v214
	v_fmac_f32_e32 v142, v241, v214
	v_fmac_f32_e32 v141, v166, v215
	v_fmac_f32_e32 v142, v242, v215
	v_fmac_f32_e32 v141, v167, v216
	v_fmac_f32_e32 v142, v243, v216
	v_add_u32_e32 v143, s100, v143
	v_add_u32_e32 v144, s100, v144
	ds_read_b128 v[172:175], v143
	ds_read_b128 v[176:179], v143 offset:16
	ds_read_b128 v[180:183], v143 offset:32
	ds_read_b128 v[164:167], v143 offset:48
	ds_read_b128 v[228:231], v144
	ds_read_b128 v[232:235], v144 offset:16
	ds_read_b128 v[236:239], v144 offset:32
	ds_read_b128 v[240:243], v144 offset:48
	v_mul_f32_e64 v41, |v141|, s61
	v_mul_f32_e64 v42, |v142|, s61
	v_exp_f32_e32 v41, v41
	v_exp_f32_e32 v42, v42
	v_min_f32_e32 v43, 0, v141
	v_min_f32_e32 v44, 0, v142
	v_add_f32_e32 v41, 1.0, v41
	v_add_f32_e32 v42, 1.0, v42
	v_cmp_gt_f32_e64 s[4:5], s24, v41
	v_cmp_gt_f32_e64 s[6:7], s24, v42
	s_nop 1
	v_cndmask_b32_e64 v45, 0, 32, s[4:5]
	v_cndmask_b32_e64 v46, 0, 32, s[6:7]
	v_ldexp_f32 v41, v41, v45
	v_ldexp_f32 v42, v42, v46
	v_log_f32_e32 v41, v41
	v_log_f32_e32 v42, v42
	v_cndmask_b32_e64 v45, 0, v192, s[4:5]
	v_cndmask_b32_e64 v46, 0, v192, s[6:7]
	v_mul_f32_e32 v47, 0x3f317217, v41
	v_mul_f32_e32 v140, 0x3f317217, v42
	v_fma_f32 v47, v41, s62, -v47
	v_fma_f32 v140, v42, s62, -v140
	v_fmac_f32_e32 v47, 0x3377d1cf, v41
	v_fmac_f32_e32 v140, 0x3377d1cf, v42
	v_fmac_f32_e32 v47, 0x3f317217, v41
	v_fmac_f32_e32 v140, 0x3f317217, v42
	v_cmp_lt_f32_e64 s[30:31], |v41|, s63
	v_cmp_lt_f32_e64 s[34:35], |v42|, s63
	s_nop 1
	v_cndmask_b32_e64 v41, v41, v47, s[30:31]
	v_cndmask_b32_e64 v42, v42, v140, s[34:35]
	v_sub_f32_e32 v41, v41, v45
	v_sub_f32_e32 v42, v42, v46
	v_sub_f32_e32 v41, v43, v41
	v_sub_f32_e32 v42, v44, v42
	v_fma_f32 v227, v41, s2, v226
	v_fma_f32 v184, v42, s2, v227
	s_waitcnt lgkmcnt(0)
	v_mov_b32_e32 v141, v38
	v_mov_b32_e32 v142, v38
	v_fmac_f32_e32 v141, v172, v201
	v_fmac_f32_e32 v142, v228, v201
	v_fmac_f32_e32 v141, v173, v202
	v_fmac_f32_e32 v142, v229, v202
	v_fmac_f32_e32 v141, v174, v203
	v_fmac_f32_e32 v142, v230, v203
	v_fmac_f32_e32 v141, v175, v204
	v_fmac_f32_e32 v142, v231, v204
	v_fmac_f32_e32 v141, v176, v205
	v_fmac_f32_e32 v142, v232, v205
	v_fmac_f32_e32 v141, v177, v206
	v_fmac_f32_e32 v142, v233, v206
	v_fmac_f32_e32 v141, v178, v207
	v_fmac_f32_e32 v142, v234, v207
	v_fmac_f32_e32 v141, v179, v208
	v_fmac_f32_e32 v142, v235, v208
	v_fmac_f32_e32 v141, v180, v209
	v_fmac_f32_e32 v142, v236, v209
	v_fmac_f32_e32 v141, v181, v210
	v_fmac_f32_e32 v142, v237, v210
	v_fmac_f32_e32 v141, v182, v211
	v_fmac_f32_e32 v142, v238, v211
	v_fmac_f32_e32 v141, v183, v212
	v_fmac_f32_e32 v142, v239, v212
	v_fmac_f32_e32 v141, v164, v213
	v_fmac_f32_e32 v142, v240, v213
	v_fmac_f32_e32 v141, v165, v214
	v_fmac_f32_e32 v142, v241, v214
	v_fmac_f32_e32 v141, v166, v215
	v_fmac_f32_e32 v142, v242, v215
	v_fmac_f32_e32 v141, v167, v216
	v_fmac_f32_e32 v142, v243, v216
	v_add_u32_e32 v143, s100, v143
	v_add_u32_e32 v144, s100, v144
	ds_read_b128 v[172:175], v143
	ds_read_b128 v[176:179], v143 offset:16
	ds_read_b128 v[180:183], v143 offset:32
	ds_read_b128 v[164:167], v143 offset:48
	ds_read_b128 v[228:231], v144
	ds_read_b128 v[232:235], v144 offset:16
	ds_read_b128 v[236:239], v144 offset:32
	ds_read_b128 v[240:243], v144 offset:48
	v_mul_f32_e64 v41, |v141|, s61
	v_mul_f32_e64 v42, |v142|, s61
	v_exp_f32_e32 v41, v41
	v_exp_f32_e32 v42, v42
	v_min_f32_e32 v43, 0, v141
	v_min_f32_e32 v44, 0, v142
	v_add_f32_e32 v41, 1.0, v41
	v_add_f32_e32 v42, 1.0, v42
	v_cmp_gt_f32_e64 s[4:5], s24, v41
	v_cmp_gt_f32_e64 s[6:7], s24, v42
	s_nop 1
	v_cndmask_b32_e64 v45, 0, 32, s[4:5]
	v_cndmask_b32_e64 v46, 0, 32, s[6:7]
	v_ldexp_f32 v41, v41, v45
	v_ldexp_f32 v42, v42, v46
	v_log_f32_e32 v41, v41
	v_log_f32_e32 v42, v42
	v_cndmask_b32_e64 v45, 0, v192, s[4:5]
	v_cndmask_b32_e64 v46, 0, v192, s[6:7]
	v_mul_f32_e32 v47, 0x3f317217, v41
	v_mul_f32_e32 v140, 0x3f317217, v42
	v_fma_f32 v47, v41, s62, -v47
	v_fma_f32 v140, v42, s62, -v140
	v_fmac_f32_e32 v47, 0x3377d1cf, v41
	v_fmac_f32_e32 v140, 0x3377d1cf, v42
	v_fmac_f32_e32 v47, 0x3f317217, v41
	v_fmac_f32_e32 v140, 0x3f317217, v42
	v_cmp_lt_f32_e64 s[30:31], |v41|, s63
	v_cmp_lt_f32_e64 s[34:35], |v42|, s63
	s_nop 1
	v_cndmask_b32_e64 v41, v41, v47, s[30:31]
	v_cndmask_b32_e64 v42, v42, v140, s[34:35]
	v_sub_f32_e32 v41, v41, v45
	v_sub_f32_e32 v42, v42, v46
	v_sub_f32_e32 v41, v43, v41
	v_sub_f32_e32 v42, v44, v42
	v_fma_f32 v185, v41, s2, v184
	v_fma_f32 v162, v42, s2, v185
	s_waitcnt lgkmcnt(0)
; __device__ __forceinline__ void gla_b(const Args& a, int l, int hd, int dir, int t0, unsigned char* sm, const bf16_t* __restrict__ PLR) {
;     ...
;     for (int k = 0; k < 16; ++k) {
;         const int s = q * 16 + k, j = dir ? 63 - s : s;
;         float x = Bs[d];
; #pragma unroll
;         for (int r = 0; r < 16; ++r) x += lrs[j * 16 + r] * W2s[r * 128 + d];
;         const float g = (fminf(x, 0.f) - __logf(1.f + __expf(-fabsf(x)))) * (1.f / 16.f);
;         run += g; Gb[j * 129 + d] = run;
;     }
;     tot[q * 128 + d] = run;
;     __syncthreads();
;     float off = 0.f;
;     for (int qq = 0; qq < q; ++qq) off += tot[qq * 128 + d];
;     if (q > 0) for (int k = 0; k < 16; ++k) { const int s = q * 16 + k, j = dir ? 63 - s : s; Gb[j * 129 + d] += off; }
	v_mov_b32_e32 v141, v38
	v_mov_b32_e32 v142, v38
	v_fmac_f32_e32 v141, v172, v201
	v_fmac_f32_e32 v142, v228, v201
	v_fmac_f32_e32 v141, v173, v202
	v_fmac_f32_e32 v142, v229, v202
	v_fmac_f32_e32 v141, v174, v203
	v_fmac_f32_e32 v142, v230, v203
	v_fmac_f32_e32 v141, v175, v204
	v_fmac_f32_e32 v142, v231, v204
	v_fmac_f32_e32 v141, v176, v205
	v_fmac_f32_e32 v142, v232, v205
	v_fmac_f32_e32 v141, v177, v206
	v_fmac_f32_e32 v142, v233, v206
	v_fmac_f32_e32 v141, v178, v207
	v_fmac_f32_e32 v142, v234, v207
	v_fmac_f32_e32 v141, v179, v208
	v_fmac_f32_e32 v142, v235, v208
	v_fmac_f32_e32 v141, v180, v209
	v_fmac_f32_e32 v142, v236, v209
	v_fmac_f32_e32 v141, v181, v210
	v_fmac_f32_e32 v142, v237, v210
	v_fmac_f32_e32 v141, v182, v211
	v_fmac_f32_e32 v142, v238, v211
	v_fmac_f32_e32 v141, v183, v212
	v_fmac_f32_e32 v142, v239, v212
	v_fmac_f32_e32 v141, v164, v213
	v_fmac_f32_e32 v142, v240, v213
	v_fmac_f32_e32 v141, v165, v214
	v_fmac_f32_e32 v142, v241, v214
	v_fmac_f32_e32 v141, v166, v215
	v_fmac_f32_e32 v142, v242, v215
	v_fmac_f32_e32 v141, v167, v216
	v_fmac_f32_e32 v142, v243, v216
	v_mul_f32_e64 v41, |v141|, s61
	v_mul_f32_e64 v42, |v142|, s61
	v_exp_f32_e32 v41, v41
	v_exp_f32_e32 v42, v42
	v_min_f32_e32 v43, 0, v141
	v_min_f32_e32 v44, 0, v142
	v_add_f32_e32 v41, 1.0, v41
	v_add_f32_e32 v42, 1.0, v42
	v_cmp_gt_f32_e64 s[4:5], s24, v41
	v_cmp_gt_f32_e64 s[6:7], s24, v42
	s_nop 1
	v_cndmask_b32_e64 v45, 0, 32, s[4:5]
	v_cndmask_b32_e64 v46, 0, 32, s[6:7]
	v_ldexp_f32 v41, v41, v45
	v_ldexp_f32 v42, v42, v46
	v_log_f32_e32 v41, v41
	v_log_f32_e32 v42, v42
	v_cndmask_b32_e64 v45, 0, v192, s[4:5]
	v_cndmask_b32_e64 v46, 0, v192, s[6:7]
	v_mul_f32_e32 v47, 0x3f317217, v41
	v_mul_f32_e32 v140, 0x3f317217, v42
	v_fma_f32 v47, v41, s62, -v47
	v_fma_f32 v140, v42, s62, -v140
	v_fmac_f32_e32 v47, 0x3377d1cf, v41
	v_fmac_f32_e32 v140, 0x3377d1cf, v42
	v_fmac_f32_e32 v47, 0x3f317217, v41
	v_fmac_f32_e32 v140, 0x3f317217, v42
	v_cmp_lt_f32_e64 s[30:31], |v41|, s63
	v_cmp_lt_f32_e64 s[34:35], |v42|, s63
	s_nop 1
	v_cndmask_b32_e64 v41, v41, v47, s[30:31]
	v_cndmask_b32_e64 v42, v42, v140, s[34:35]
	v_sub_f32_e32 v41, v41, v45
	v_sub_f32_e32 v42, v42, v46
	v_sub_f32_e32 v41, v43, v41
	v_sub_f32_e32 v42, v44, v42
	v_fma_f32 v163, v41, s2, v162
	v_fma_f32 v168, v42, s2, v163
	ds_write_b32 v33, v168 offset:45824
	s_waitcnt lgkmcnt(0)
	s_barrier
	ds_read_b32 v41, v32 offset:45824
	ds_read_b32 v42, v32 offset:46336
	ds_read_b32 v43, v32 offset:46848
	v_lshrrev_b32_e32 v39, 7, v171
	v_cmp_lt_u32_e64 s[4:5], 0, v39
	v_cmp_lt_u32_e64 s[6:7], 1, v39
	v_cmp_lt_u32_e64 s[30:31], 2, v39
	s_waitcnt lgkmcnt(0)
	v_cndmask_b32_e64 v41, 0, v41, s[4:5]
	v_cndmask_b32_e64 v42, 0, v42, s[6:7]
	v_cndmask_b32_e64 v43, 0, v43, s[30:31]
	v_add_f32_e32 v41, v41, v42
	v_add_f32_e32 v41, v41, v43
	v_add_f32_e32 v45, v217, v41
	ds_write_b32 v40, v45
	v_add_u32_e32 v40, s101, v40
	v_add_f32_e32 v46, v218, v41
	ds_write_b32 v40, v46
	v_add_u32_e32 v40, s101, v40
	v_add_f32_e32 v45, v219, v41
	ds_write_b32 v40, v45
	v_add_u32_e32 v40, s101, v40
	v_add_f32_e32 v46, v220, v41
	ds_write_b32 v40, v46
	v_add_u32_e32 v40, s101, v40
	v_add_f32_e32 v45, v221, v41
	ds_write_b32 v40, v45
	v_add_u32_e32 v40, s101, v40
	v_add_f32_e32 v46, v222, v41
	ds_write_b32 v40, v46
	v_add_u32_e32 v40, s101, v40
	v_add_f32_e32 v45, v223, v41
	ds_write_b32 v40, v45
	v_add_u32_e32 v40, s101, v40
	v_add_f32_e32 v46, v224, v41
	ds_write_b32 v40, v46
	v_add_u32_e32 v40, s101, v40
	v_add_f32_e32 v45, v225, v41
	ds_write_b32 v40, v45
	v_add_u32_e32 v40, s101, v40
	v_add_f32_e32 v46, v226, v41
	ds_write_b32 v40, v46
	v_add_u32_e32 v40, s101, v40
	v_add_f32_e32 v45, v227, v41
	ds_write_b32 v40, v45
	v_add_u32_e32 v40, s101, v40
	v_add_f32_e32 v46, v184, v41
	ds_write_b32 v40, v46
	v_add_u32_e32 v40, s101, v40
	v_add_f32_e32 v45, v185, v41
	ds_write_b32 v40, v45
	v_add_u32_e32 v40, s101, v40
	v_add_f32_e32 v46, v162, v41
	ds_write_b32 v40, v46
	v_add_u32_e32 v40, s101, v40
	v_add_f32_e32 v45, v163, v41
	ds_write_b32 v40, v45
	v_add_u32_e32 v40, s101, v40
	v_add_f32_e32 v46, v168, v41
	ds_write_b32 v40, v46
	s_waitcnt vmcnt(0)
	s_mov_b64 s[4:5], exec
